# RWKV scanner chunk loop rewritten by hand: operand LDS prefetch interleaved with math, joint d1/d2 packed accumulation (20 VALU/step), producer writes (nkk,wr) interleaved
# baseline (speedup 1.0000x reference)
.Lstag_done:
	s_and_b32 s1, s0, 1
	s_lshl_b32 s31, s1, 8
	s_mul_i32 s30, s1, 0xa000
	s_add_i32 s31, s31, 0x18000
	v_add_u32_e32 v6, s30, v151
	v_mov_b32_e32 v8, s31
	v_lshl_add_u32 v7, s1, 13, v0
	v_lshl_add_u32 v9, s1, 11, v39
	v_add_u32_e32 v22, 0x400, v9
	ds_read_b128 v[58:61], v6
	ds_read_b128 v[62:65], v6 offset:16
	ds_read_b128 v[66:69], v6 offset:32
	ds_read_b128 v[70:73], v6 offset:48
	ds_read_b128 v[74:77], v6 offset:64
	ds_read2st64_b32 v[118:119], v7 offset1:1
	ds_read_b128 v[120:123], v8
	ds_read_b128 v[78:81], v6 offset:1280
	ds_read_b128 v[82:85], v6 offset:1296
	ds_read_b128 v[86:89], v6 offset:1312
	ds_read_b128 v[90:93], v6 offset:1328
	ds_read_b128 v[94:97], v6 offset:1344
	s_waitcnt lgkmcnt(5)
	v_pk_mul_f32 v[10:11], v[2:3], v[58:59] op_sel_hi:[0,1]
	ds_read_b128 v[98:101], v6 offset:2560
	v_pk_mul_f32 v[18:19], v[74:75], v[118:119] op_sel_hi:[1,0]
	v_pk_fma_f32 v[10:11], v[2:3], v[60:61], v[10:11] op_sel:[1,0,0] op_sel_hi:[1,1,1]
	ds_read_b128 v[102:105], v6 offset:2576
	v_pk_mul_f32 v[20:21], v[76:77], v[118:119] op_sel_hi:[1,0]
	v_pk_fma_f32 v[10:11], v[4:5], v[62:63], v[10:11] op_sel_hi:[0,1,1]
	ds_read_b128 v[106:109], v6 offset:2592
	v_pk_fma_f32 v[18:19], v[2:3], v[66:67], v[18:19]
	v_pk_fma_f32 v[10:11], v[4:5], v[64:65], v[10:11] op_sel:[1,0,0] op_sel_hi:[1,1,1]
	v_pk_fma_f32 v[20:21], v[4:5], v[68:69], v[20:21]
	ds_read_b128 v[110:113], v6 offset:2608
	v_add_f32_dpp v10, v10, v10 quad_perm:[1,0,3,2] row_mask:0xf bank_mask:0xf bound_ctrl:1
	v_add_f32_dpp v11, v11, v11 quad_perm:[1,0,3,2] row_mask:0xf bank_mask:0xf bound_ctrl:1
	ds_read_b128 v[114:117], v6 offset:2624
	v_add_f32_dpp v10, v10, v10 quad_perm:[2,3,0,1] row_mask:0xf bank_mask:0xf bound_ctrl:1
	v_add_f32_dpp v11, v11, v11 quad_perm:[2,3,0,1] row_mask:0xf bank_mask:0xf bound_ctrl:1
	ds_read2st64_b32 v[206:207], v7 offset0:2 offset1:3
	v_add_f32_dpp v10, v10, v10 row_half_mirror row_mask:0xf bank_mask:0xf bound_ctrl:1
	v_add_f32_dpp v11, v11, v11 row_half_mirror row_mask:0xf bank_mask:0xf bound_ctrl:1
	ds_read_b128 v[208:211], v8 offset:16
	v_add_f32_dpp v10, v10, v10 row_mirror row_mask:0xf bank_mask:0xf bound_ctrl:1
	v_add_f32_dpp v11, v11, v11 row_mirror row_mask:0xf bank_mask:0xf bound_ctrl:1
	v_pk_fma_f32 v[2:3], v[70:71], v[10:11], v[18:19] op_sel_hi:[1,0,1]
	v_pk_fma_f32 v[4:5], v[72:73], v[10:11], v[20:21] op_sel_hi:[1,0,1]
	s_waitcnt lgkmcnt(7)
	v_pk_mul_f32 v[12:13], v[2:3], v[78:79] op_sel_hi:[0,1]
	ds_read_b128 v[186:189], v6 offset:3840
	v_pk_mul_f32 v[18:19], v[94:95], v[118:119] op_sel:[0,1] op_sel_hi:[1,1]
	v_pk_fma_f32 v[12:13], v[2:3], v[80:81], v[12:13] op_sel:[1,0,0] op_sel_hi:[1,1,1]
	ds_read_b128 v[190:193], v6 offset:3856
	v_pk_mul_f32 v[20:21], v[96:97], v[118:119] op_sel:[0,1] op_sel_hi:[1,1]
	v_pk_fma_f32 v[12:13], v[4:5], v[82:83], v[12:13] op_sel_hi:[0,1,1]
	ds_read_b128 v[194:197], v6 offset:3872
	v_pk_fma_f32 v[18:19], v[2:3], v[86:87], v[18:19]
	v_pk_fma_f32 v[12:13], v[4:5], v[84:85], v[12:13] op_sel:[1,0,0] op_sel_hi:[1,1,1]
	v_pk_fma_f32 v[20:21], v[4:5], v[88:89], v[20:21]
	v_fmac_f32_e32 v11, v120, v10
	v_add_f32_dpp v12, v12, v12 quad_perm:[1,0,3,2] row_mask:0xf bank_mask:0xf bound_ctrl:1
	v_add_f32_dpp v13, v13, v13 quad_perm:[1,0,3,2] row_mask:0xf bank_mask:0xf bound_ctrl:1
	v_fmac_f32_e32 v11, v118, v121
	ds_read_b128 v[198:201], v6 offset:3888
	v_add_f32_dpp v12, v12, v12 quad_perm:[2,3,0,1] row_mask:0xf bank_mask:0xf bound_ctrl:1
	v_add_f32_dpp v13, v13, v13 quad_perm:[2,3,0,1] row_mask:0xf bank_mask:0xf bound_ctrl:1
	ds_read_b128 v[202:205], v6 offset:3904
	v_add_f32_dpp v12, v12, v12 row_half_mirror row_mask:0xf bank_mask:0xf bound_ctrl:1
	v_add_f32_dpp v13, v13, v13 row_half_mirror row_mask:0xf bank_mask:0xf bound_ctrl:1
	s_nop 0
	v_add_f32_dpp v12, v12, v12 row_mirror row_mask:0xf bank_mask:0xf bound_ctrl:1
	v_add_f32_dpp v13, v13, v13 row_mirror row_mask:0xf bank_mask:0xf bound_ctrl:1
	v_pk_fma_f32 v[2:3], v[90:91], v[12:13], v[18:19] op_sel_hi:[1,0,1]
	v_pk_fma_f32 v[4:5], v[92:93], v[12:13], v[20:21] op_sel_hi:[1,0,1]
	s_waitcnt lgkmcnt(5)
	v_pk_mul_f32 v[14:15], v[2:3], v[98:99] op_sel_hi:[0,1]
	ds_read_b128 v[58:61], v6 offset:5120
	v_pk_mul_f32 v[18:19], v[114:115], v[206:207] op_sel_hi:[1,0]
	v_pk_fma_f32 v[14:15], v[2:3], v[100:101], v[14:15] op_sel:[1,0,0] op_sel_hi:[1,1,1]
	ds_read_b128 v[62:65], v6 offset:5136
	v_pk_mul_f32 v[20:21], v[116:117], v[206:207] op_sel_hi:[1,0]
	v_pk_fma_f32 v[14:15], v[4:5], v[102:103], v[14:15] op_sel_hi:[0,1,1]
	ds_read_b128 v[66:69], v6 offset:5152
	v_pk_fma_f32 v[18:19], v[2:3], v[106:107], v[18:19]
	v_pk_fma_f32 v[14:15], v[4:5], v[104:105], v[14:15] op_sel:[1,0,0] op_sel_hi:[1,1,1]
	v_pk_fma_f32 v[20:21], v[4:5], v[108:109], v[20:21]
	v_fmac_f32_e32 v13, v122, v12
	v_add_f32_dpp v14, v14, v14 quad_perm:[1,0,3,2] row_mask:0xf bank_mask:0xf bound_ctrl:1
	v_add_f32_dpp v15, v15, v15 quad_perm:[1,0,3,2] row_mask:0xf bank_mask:0xf bound_ctrl:1
	v_fmac_f32_e32 v13, v119, v123
	ds_write2_b32 v9, v11, v13 offset1:16
	v_add_f32_dpp v14, v14, v14 quad_perm:[2,3,0,1] row_mask:0xf bank_mask:0xf bound_ctrl:1
	v_add_f32_dpp v15, v15, v15 quad_perm:[2,3,0,1] row_mask:0xf bank_mask:0xf bound_ctrl:1
	ds_read_b128 v[70:73], v6 offset:5168
	v_add_f32_dpp v14, v14, v14 row_half_mirror row_mask:0xf bank_mask:0xf bound_ctrl:1
	v_add_f32_dpp v15, v15, v15 row_half_mirror row_mask:0xf bank_mask:0xf bound_ctrl:1
	ds_read_b128 v[74:77], v6 offset:5184
	v_add_f32_dpp v14, v14, v14 row_mirror row_mask:0xf bank_mask:0xf bound_ctrl:1
	v_add_f32_dpp v15, v15, v15 row_mirror row_mask:0xf bank_mask:0xf bound_ctrl:1
	v_pk_fma_f32 v[2:3], v[110:111], v[14:15], v[18:19] op_sel_hi:[1,0,1]
	v_pk_fma_f32 v[4:5], v[112:113], v[14:15], v[20:21] op_sel_hi:[1,0,1]
	ds_read2st64_b32 v[118:119], v7 offset0:4 offset1:5
	ds_read_b128 v[120:123], v8 offset:32
	s_waitcnt lgkmcnt(8)
	v_pk_mul_f32 v[16:17], v[2:3], v[186:187] op_sel_hi:[0,1]
	ds_read_b128 v[78:81], v6 offset:6400
	v_pk_mul_f32 v[18:19], v[202:203], v[206:207] op_sel:[0,1] op_sel_hi:[1,1]
	v_pk_fma_f32 v[16:17], v[2:3], v[188:189], v[16:17] op_sel:[1,0,0] op_sel_hi:[1,1,1]
	ds_read_b128 v[82:85], v6 offset:6416
	v_pk_mul_f32 v[20:21], v[204:205], v[206:207] op_sel:[0,1] op_sel_hi:[1,1]
	v_pk_fma_f32 v[16:17], v[4:5], v[190:191], v[16:17] op_sel_hi:[0,1,1]
	ds_read_b128 v[86:89], v6 offset:6432
	v_pk_fma_f32 v[18:19], v[2:3], v[194:195], v[18:19]
	v_pk_fma_f32 v[16:17], v[4:5], v[192:193], v[16:17] op_sel:[1,0,0] op_sel_hi:[1,1,1]
	v_pk_fma_f32 v[20:21], v[4:5], v[196:197], v[20:21]
	v_fmac_f32_e32 v15, v208, v14
	v_add_f32_dpp v16, v16, v16 quad_perm:[1,0,3,2] row_mask:0xf bank_mask:0xf bound_ctrl:1
	v_add_f32_dpp v17, v17, v17 quad_perm:[1,0,3,2] row_mask:0xf bank_mask:0xf bound_ctrl:1
	v_fmac_f32_e32 v15, v206, v209
	ds_read_b128 v[90:93], v6 offset:6448
	v_add_f32_dpp v16, v16, v16 quad_perm:[2,3,0,1] row_mask:0xf bank_mask:0xf bound_ctrl:1
	v_add_f32_dpp v17, v17, v17 quad_perm:[2,3,0,1] row_mask:0xf bank_mask:0xf bound_ctrl:1
	ds_read_b128 v[94:97], v6 offset:6464
	v_add_f32_dpp v16, v16, v16 row_half_mirror row_mask:0xf bank_mask:0xf bound_ctrl:1
	v_add_f32_dpp v17, v17, v17 row_half_mirror row_mask:0xf bank_mask:0xf bound_ctrl:1
	s_nop 0
	v_add_f32_dpp v16, v16, v16 row_mirror row_mask:0xf bank_mask:0xf bound_ctrl:1
	v_add_f32_dpp v17, v17, v17 row_mirror row_mask:0xf bank_mask:0xf bound_ctrl:1
	v_pk_fma_f32 v[2:3], v[198:199], v[16:17], v[18:19] op_sel_hi:[1,0,1]
	v_pk_fma_f32 v[4:5], v[200:201], v[16:17], v[20:21] op_sel_hi:[1,0,1]
	s_waitcnt lgkmcnt(5)
	v_pk_mul_f32 v[10:11], v[2:3], v[58:59] op_sel_hi:[0,1]
	ds_read_b128 v[98:101], v6 offset:7680
	v_pk_mul_f32 v[18:19], v[74:75], v[118:119] op_sel_hi:[1,0]
	v_pk_fma_f32 v[10:11], v[2:3], v[60:61], v[10:11] op_sel:[1,0,0] op_sel_hi:[1,1,1]
	ds_read_b128 v[102:105], v6 offset:7696
	v_pk_mul_f32 v[20:21], v[76:77], v[118:119] op_sel_hi:[1,0]
	v_pk_fma_f32 v[10:11], v[4:5], v[62:63], v[10:11] op_sel_hi:[0,1,1]
	ds_read_b128 v[106:109], v6 offset:7712
	v_pk_fma_f32 v[18:19], v[2:3], v[66:67], v[18:19]
	v_pk_fma_f32 v[10:11], v[4:5], v[64:65], v[10:11] op_sel:[1,0,0] op_sel_hi:[1,1,1]
	v_pk_fma_f32 v[20:21], v[4:5], v[68:69], v[20:21]
	v_fmac_f32_e32 v17, v210, v16
	v_add_f32_dpp v10, v10, v10 quad_perm:[1,0,3,2] row_mask:0xf bank_mask:0xf bound_ctrl:1
	v_add_f32_dpp v11, v11, v11 quad_perm:[1,0,3,2] row_mask:0xf bank_mask:0xf bound_ctrl:1
	v_fmac_f32_e32 v17, v207, v211
	ds_write2_b32 v9, v15, v17 offset0:32 offset1:48
	v_add_f32_dpp v10, v10, v10 quad_perm:[2,3,0,1] row_mask:0xf bank_mask:0xf bound_ctrl:1
	v_add_f32_dpp v11, v11, v11 quad_perm:[2,3,0,1] row_mask:0xf bank_mask:0xf bound_ctrl:1
	ds_read_b128 v[110:113], v6 offset:7728
	v_add_f32_dpp v10, v10, v10 row_half_mirror row_mask:0xf bank_mask:0xf bound_ctrl:1
	v_add_f32_dpp v11, v11, v11 row_half_mirror row_mask:0xf bank_mask:0xf bound_ctrl:1
	ds_read_b128 v[114:117], v6 offset:7744
	v_add_f32_dpp v10, v10, v10 row_mirror row_mask:0xf bank_mask:0xf bound_ctrl:1
	v_add_f32_dpp v11, v11, v11 row_mirror row_mask:0xf bank_mask:0xf bound_ctrl:1
	v_pk_fma_f32 v[2:3], v[70:71], v[10:11], v[18:19] op_sel_hi:[1,0,1]
	v_pk_fma_f32 v[4:5], v[72:73], v[10:11], v[20:21] op_sel_hi:[1,0,1]
	ds_read2st64_b32 v[206:207], v7 offset0:6 offset1:7
	ds_read_b128 v[208:211], v8 offset:48
	s_waitcnt lgkmcnt(8)
	v_pk_mul_f32 v[12:13], v[2:3], v[78:79] op_sel_hi:[0,1]
	ds_read_b128 v[186:189], v6 offset:8960
	v_pk_mul_f32 v[18:19], v[94:95], v[118:119] op_sel:[0,1] op_sel_hi:[1,1]
	v_pk_fma_f32 v[12:13], v[2:3], v[80:81], v[12:13] op_sel:[1,0,0] op_sel_hi:[1,1,1]
	ds_read_b128 v[190:193], v6 offset:8976
	v_pk_mul_f32 v[20:21], v[96:97], v[118:119] op_sel:[0,1] op_sel_hi:[1,1]
	v_pk_fma_f32 v[12:13], v[4:5], v[82:83], v[12:13] op_sel_hi:[0,1,1]
	ds_read_b128 v[194:197], v6 offset:8992
	v_pk_fma_f32 v[18:19], v[2:3], v[86:87], v[18:19]
	v_pk_fma_f32 v[12:13], v[4:5], v[84:85], v[12:13] op_sel:[1,0,0] op_sel_hi:[1,1,1]
	v_pk_fma_f32 v[20:21], v[4:5], v[88:89], v[20:21]
	v_fmac_f32_e32 v11, v120, v10
	v_add_f32_dpp v12, v12, v12 quad_perm:[1,0,3,2] row_mask:0xf bank_mask:0xf bound_ctrl:1
	v_add_f32_dpp v13, v13, v13 quad_perm:[1,0,3,2] row_mask:0xf bank_mask:0xf bound_ctrl:1
	v_fmac_f32_e32 v11, v118, v121
	ds_read_b128 v[198:201], v6 offset:9008
	v_add_f32_dpp v12, v12, v12 quad_perm:[2,3,0,1] row_mask:0xf bank_mask:0xf bound_ctrl:1
	v_add_f32_dpp v13, v13, v13 quad_perm:[2,3,0,1] row_mask:0xf bank_mask:0xf bound_ctrl:1
	ds_read_b128 v[202:205], v6 offset:9024
	v_add_f32_dpp v12, v12, v12 row_half_mirror row_mask:0xf bank_mask:0xf bound_ctrl:1
	v_add_f32_dpp v13, v13, v13 row_half_mirror row_mask:0xf bank_mask:0xf bound_ctrl:1
	s_nop 0
	v_add_f32_dpp v12, v12, v12 row_mirror row_mask:0xf bank_mask:0xf bound_ctrl:1
	v_add_f32_dpp v13, v13, v13 row_mirror row_mask:0xf bank_mask:0xf bound_ctrl:1
	v_pk_fma_f32 v[2:3], v[90:91], v[12:13], v[18:19] op_sel_hi:[1,0,1]
	v_pk_fma_f32 v[4:5], v[92:93], v[12:13], v[20:21] op_sel_hi:[1,0,1]
	s_waitcnt lgkmcnt(5)
	v_pk_mul_f32 v[14:15], v[2:3], v[98:99] op_sel_hi:[0,1]
	ds_read_b128 v[58:61], v6 offset:10240
	v_pk_mul_f32 v[18:19], v[114:115], v[206:207] op_sel_hi:[1,0]
	v_pk_fma_f32 v[14:15], v[2:3], v[100:101], v[14:15] op_sel:[1,0,0] op_sel_hi:[1,1,1]
	ds_read_b128 v[62:65], v6 offset:10256
	v_pk_mul_f32 v[20:21], v[116:117], v[206:207] op_sel_hi:[1,0]
	v_pk_fma_f32 v[14:15], v[4:5], v[102:103], v[14:15] op_sel_hi:[0,1,1]
	ds_read_b128 v[66:69], v6 offset:10272
	v_pk_fma_f32 v[18:19], v[2:3], v[106:107], v[18:19]
	v_pk_fma_f32 v[14:15], v[4:5], v[104:105], v[14:15] op_sel:[1,0,0] op_sel_hi:[1,1,1]
	v_pk_fma_f32 v[20:21], v[4:5], v[108:109], v[20:21]
	v_fmac_f32_e32 v13, v122, v12
	v_add_f32_dpp v14, v14, v14 quad_perm:[1,0,3,2] row_mask:0xf bank_mask:0xf bound_ctrl:1
	v_add_f32_dpp v15, v15, v15 quad_perm:[1,0,3,2] row_mask:0xf bank_mask:0xf bound_ctrl:1
	v_fmac_f32_e32 v13, v119, v123
	ds_write2_b32 v9, v11, v13 offset0:64 offset1:80
	v_add_f32_dpp v14, v14, v14 quad_perm:[2,3,0,1] row_mask:0xf bank_mask:0xf bound_ctrl:1
	v_add_f32_dpp v15, v15, v15 quad_perm:[2,3,0,1] row_mask:0xf bank_mask:0xf bound_ctrl:1
	ds_read_b128 v[70:73], v6 offset:10288
	v_add_f32_dpp v14, v14, v14 row_half_mirror row_mask:0xf bank_mask:0xf bound_ctrl:1
	v_add_f32_dpp v15, v15, v15 row_half_mirror row_mask:0xf bank_mask:0xf bound_ctrl:1
	ds_read_b128 v[74:77], v6 offset:10304
	v_add_f32_dpp v14, v14, v14 row_mirror row_mask:0xf bank_mask:0xf bound_ctrl:1
	v_add_f32_dpp v15, v15, v15 row_mirror row_mask:0xf bank_mask:0xf bound_ctrl:1
	v_pk_fma_f32 v[2:3], v[110:111], v[14:15], v[18:19] op_sel_hi:[1,0,1]
	v_pk_fma_f32 v[4:5], v[112:113], v[14:15], v[20:21] op_sel_hi:[1,0,1]
	ds_read2st64_b32 v[118:119], v7 offset0:8 offset1:9
	ds_read_b128 v[120:123], v8 offset:64
	s_waitcnt lgkmcnt(8)
	v_pk_mul_f32 v[16:17], v[2:3], v[186:187] op_sel_hi:[0,1]
	ds_read_b128 v[78:81], v6 offset:11520
	v_pk_mul_f32 v[18:19], v[202:203], v[206:207] op_sel:[0,1] op_sel_hi:[1,1]
	v_pk_fma_f32 v[16:17], v[2:3], v[188:189], v[16:17] op_sel:[1,0,0] op_sel_hi:[1,1,1]
	ds_read_b128 v[82:85], v6 offset:11536
	v_pk_mul_f32 v[20:21], v[204:205], v[206:207] op_sel:[0,1] op_sel_hi:[1,1]
	v_pk_fma_f32 v[16:17], v[4:5], v[190:191], v[16:17] op_sel_hi:[0,1,1]
	ds_read_b128 v[86:89], v6 offset:11552
	v_pk_fma_f32 v[18:19], v[2:3], v[194:195], v[18:19]
	v_pk_fma_f32 v[16:17], v[4:5], v[192:193], v[16:17] op_sel:[1,0,0] op_sel_hi:[1,1,1]
	v_pk_fma_f32 v[20:21], v[4:5], v[196:197], v[20:21]
	v_fmac_f32_e32 v15, v208, v14
	v_add_f32_dpp v16, v16, v16 quad_perm:[1,0,3,2] row_mask:0xf bank_mask:0xf bound_ctrl:1
	v_add_f32_dpp v17, v17, v17 quad_perm:[1,0,3,2] row_mask:0xf bank_mask:0xf bound_ctrl:1
	v_fmac_f32_e32 v15, v206, v209
	ds_read_b128 v[90:93], v6 offset:11568
	v_add_f32_dpp v16, v16, v16 quad_perm:[2,3,0,1] row_mask:0xf bank_mask:0xf bound_ctrl:1
	v_add_f32_dpp v17, v17, v17 quad_perm:[2,3,0,1] row_mask:0xf bank_mask:0xf bound_ctrl:1
	ds_read_b128 v[94:97], v6 offset:11584
	v_add_f32_dpp v16, v16, v16 row_half_mirror row_mask:0xf bank_mask:0xf bound_ctrl:1
	v_add_f32_dpp v17, v17, v17 row_half_mirror row_mask:0xf bank_mask:0xf bound_ctrl:1
	s_nop 0
	v_add_f32_dpp v16, v16, v16 row_mirror row_mask:0xf bank_mask:0xf bound_ctrl:1
	v_add_f32_dpp v17, v17, v17 row_mirror row_mask:0xf bank_mask:0xf bound_ctrl:1
	v_pk_fma_f32 v[2:3], v[198:199], v[16:17], v[18:19] op_sel_hi:[1,0,1]
	v_pk_fma_f32 v[4:5], v[200:201], v[16:17], v[20:21] op_sel_hi:[1,0,1]
	s_waitcnt lgkmcnt(5)
	v_pk_mul_f32 v[10:11], v[2:3], v[58:59] op_sel_hi:[0,1]
	ds_read_b128 v[98:101], v6 offset:12800
	v_pk_mul_f32 v[18:19], v[74:75], v[118:119] op_sel_hi:[1,0]
	v_pk_fma_f32 v[10:11], v[2:3], v[60:61], v[10:11] op_sel:[1,0,0] op_sel_hi:[1,1,1]
	ds_read_b128 v[102:105], v6 offset:12816
	v_pk_mul_f32 v[20:21], v[76:77], v[118:119] op_sel_hi:[1,0]
	v_pk_fma_f32 v[10:11], v[4:5], v[62:63], v[10:11] op_sel_hi:[0,1,1]
	ds_read_b128 v[106:109], v6 offset:12832
	v_pk_fma_f32 v[18:19], v[2:3], v[66:67], v[18:19]
	v_pk_fma_f32 v[10:11], v[4:5], v[64:65], v[10:11] op_sel:[1,0,0] op_sel_hi:[1,1,1]
	v_pk_fma_f32 v[20:21], v[4:5], v[68:69], v[20:21]
	v_fmac_f32_e32 v17, v210, v16
	v_add_f32_dpp v10, v10, v10 quad_perm:[1,0,3,2] row_mask:0xf bank_mask:0xf bound_ctrl:1
	v_add_f32_dpp v11, v11, v11 quad_perm:[1,0,3,2] row_mask:0xf bank_mask:0xf bound_ctrl:1
	v_fmac_f32_e32 v17, v207, v211
	ds_write2_b32 v9, v15, v17 offset0:96 offset1:112
	v_add_f32_dpp v10, v10, v10 quad_perm:[2,3,0,1] row_mask:0xf bank_mask:0xf bound_ctrl:1
	v_add_f32_dpp v11, v11, v11 quad_perm:[2,3,0,1] row_mask:0xf bank_mask:0xf bound_ctrl:1
	ds_read_b128 v[110:113], v6 offset:12848
	v_add_f32_dpp v10, v10, v10 row_half_mirror row_mask:0xf bank_mask:0xf bound_ctrl:1
	v_add_f32_dpp v11, v11, v11 row_half_mirror row_mask:0xf bank_mask:0xf bound_ctrl:1
	ds_read_b128 v[114:117], v6 offset:12864
	v_add_f32_dpp v10, v10, v10 row_mirror row_mask:0xf bank_mask:0xf bound_ctrl:1
	v_add_f32_dpp v11, v11, v11 row_mirror row_mask:0xf bank_mask:0xf bound_ctrl:1
	v_pk_fma_f32 v[2:3], v[70:71], v[10:11], v[18:19] op_sel_hi:[1,0,1]
	v_pk_fma_f32 v[4:5], v[72:73], v[10:11], v[20:21] op_sel_hi:[1,0,1]
	ds_read2st64_b32 v[206:207], v7 offset0:10 offset1:11
	ds_read_b128 v[208:211], v8 offset:80
	s_waitcnt lgkmcnt(8)
	v_pk_mul_f32 v[12:13], v[2:3], v[78:79] op_sel_hi:[0,1]
	ds_read_b128 v[186:189], v6 offset:14080
	v_pk_mul_f32 v[18:19], v[94:95], v[118:119] op_sel:[0,1] op_sel_hi:[1,1]
	v_pk_fma_f32 v[12:13], v[2:3], v[80:81], v[12:13] op_sel:[1,0,0] op_sel_hi:[1,1,1]
	ds_read_b128 v[190:193], v6 offset:14096
	v_pk_mul_f32 v[20:21], v[96:97], v[118:119] op_sel:[0,1] op_sel_hi:[1,1]
	v_pk_fma_f32 v[12:13], v[4:5], v[82:83], v[12:13] op_sel_hi:[0,1,1]
	ds_read_b128 v[194:197], v6 offset:14112
	v_pk_fma_f32 v[18:19], v[2:3], v[86:87], v[18:19]
	v_pk_fma_f32 v[12:13], v[4:5], v[84:85], v[12:13] op_sel:[1,0,0] op_sel_hi:[1,1,1]
	v_pk_fma_f32 v[20:21], v[4:5], v[88:89], v[20:21]
	v_fmac_f32_e32 v11, v120, v10
	v_add_f32_dpp v12, v12, v12 quad_perm:[1,0,3,2] row_mask:0xf bank_mask:0xf bound_ctrl:1
	v_add_f32_dpp v13, v13, v13 quad_perm:[1,0,3,2] row_mask:0xf bank_mask:0xf bound_ctrl:1
	v_fmac_f32_e32 v11, v118, v121
	ds_read_b128 v[198:201], v6 offset:14128
	v_add_f32_dpp v12, v12, v12 quad_perm:[2,3,0,1] row_mask:0xf bank_mask:0xf bound_ctrl:1
	v_add_f32_dpp v13, v13, v13 quad_perm:[2,3,0,1] row_mask:0xf bank_mask:0xf bound_ctrl:1
	ds_read_b128 v[202:205], v6 offset:14144
	v_add_f32_dpp v12, v12, v12 row_half_mirror row_mask:0xf bank_mask:0xf bound_ctrl:1
	v_add_f32_dpp v13, v13, v13 row_half_mirror row_mask:0xf bank_mask:0xf bound_ctrl:1
	s_nop 0
	v_add_f32_dpp v12, v12, v12 row_mirror row_mask:0xf bank_mask:0xf bound_ctrl:1
	v_add_f32_dpp v13, v13, v13 row_mirror row_mask:0xf bank_mask:0xf bound_ctrl:1
	v_pk_fma_f32 v[2:3], v[90:91], v[12:13], v[18:19] op_sel_hi:[1,0,1]
	v_pk_fma_f32 v[4:5], v[92:93], v[12:13], v[20:21] op_sel_hi:[1,0,1]
	s_waitcnt lgkmcnt(5)
	v_pk_mul_f32 v[14:15], v[2:3], v[98:99] op_sel_hi:[0,1]
	ds_read_b128 v[58:61], v6 offset:15360
	v_pk_mul_f32 v[18:19], v[114:115], v[206:207] op_sel_hi:[1,0]
	v_pk_fma_f32 v[14:15], v[2:3], v[100:101], v[14:15] op_sel:[1,0,0] op_sel_hi:[1,1,1]
	ds_read_b128 v[62:65], v6 offset:15376
	v_pk_mul_f32 v[20:21], v[116:117], v[206:207] op_sel_hi:[1,0]
	v_pk_fma_f32 v[14:15], v[4:5], v[102:103], v[14:15] op_sel_hi:[0,1,1]
	ds_read_b128 v[66:69], v6 offset:15392
	v_pk_fma_f32 v[18:19], v[2:3], v[106:107], v[18:19]
	v_pk_fma_f32 v[14:15], v[4:5], v[104:105], v[14:15] op_sel:[1,0,0] op_sel_hi:[1,1,1]
	v_pk_fma_f32 v[20:21], v[4:5], v[108:109], v[20:21]
	v_fmac_f32_e32 v13, v122, v12
	v_add_f32_dpp v14, v14, v14 quad_perm:[1,0,3,2] row_mask:0xf bank_mask:0xf bound_ctrl:1
	v_add_f32_dpp v15, v15, v15 quad_perm:[1,0,3,2] row_mask:0xf bank_mask:0xf bound_ctrl:1
	v_fmac_f32_e32 v13, v119, v123
	ds_write2_b32 v9, v11, v13 offset0:128 offset1:144
	v_add_f32_dpp v14, v14, v14 quad_perm:[2,3,0,1] row_mask:0xf bank_mask:0xf bound_ctrl:1
	v_add_f32_dpp v15, v15, v15 quad_perm:[2,3,0,1] row_mask:0xf bank_mask:0xf bound_ctrl:1
	ds_read_b128 v[70:73], v6 offset:15408
	v_add_f32_dpp v14, v14, v14 row_half_mirror row_mask:0xf bank_mask:0xf bound_ctrl:1
	v_add_f32_dpp v15, v15, v15 row_half_mirror row_mask:0xf bank_mask:0xf bound_ctrl:1
	ds_read_b128 v[74:77], v6 offset:15424
	v_add_f32_dpp v14, v14, v14 row_mirror row_mask:0xf bank_mask:0xf bound_ctrl:1
	v_add_f32_dpp v15, v15, v15 row_mirror row_mask:0xf bank_mask:0xf bound_ctrl:1
	v_pk_fma_f32 v[2:3], v[110:111], v[14:15], v[18:19] op_sel_hi:[1,0,1]
	v_pk_fma_f32 v[4:5], v[112:113], v[14:15], v[20:21] op_sel_hi:[1,0,1]
	ds_read2st64_b32 v[118:119], v7 offset0:12 offset1:13
	ds_read_b128 v[120:123], v8 offset:96
	s_waitcnt lgkmcnt(8)
	v_pk_mul_f32 v[16:17], v[2:3], v[186:187] op_sel_hi:[0,1]
	ds_read_b128 v[78:81], v6 offset:16640
	v_pk_mul_f32 v[18:19], v[202:203], v[206:207] op_sel:[0,1] op_sel_hi:[1,1]
	v_pk_fma_f32 v[16:17], v[2:3], v[188:189], v[16:17] op_sel:[1,0,0] op_sel_hi:[1,1,1]
	ds_read_b128 v[82:85], v6 offset:16656
	v_pk_mul_f32 v[20:21], v[204:205], v[206:207] op_sel:[0,1] op_sel_hi:[1,1]
	v_pk_fma_f32 v[16:17], v[4:5], v[190:191], v[16:17] op_sel_hi:[0,1,1]
	ds_read_b128 v[86:89], v6 offset:16672
	v_pk_fma_f32 v[18:19], v[2:3], v[194:195], v[18:19]
	v_pk_fma_f32 v[16:17], v[4:5], v[192:193], v[16:17] op_sel:[1,0,0] op_sel_hi:[1,1,1]
	v_pk_fma_f32 v[20:21], v[4:5], v[196:197], v[20:21]
	v_fmac_f32_e32 v15, v208, v14
	v_add_f32_dpp v16, v16, v16 quad_perm:[1,0,3,2] row_mask:0xf bank_mask:0xf bound_ctrl:1
	v_add_f32_dpp v17, v17, v17 quad_perm:[1,0,3,2] row_mask:0xf bank_mask:0xf bound_ctrl:1
	v_fmac_f32_e32 v15, v206, v209
	ds_read_b128 v[90:93], v6 offset:16688
	v_add_f32_dpp v16, v16, v16 quad_perm:[2,3,0,1] row_mask:0xf bank_mask:0xf bound_ctrl:1
	v_add_f32_dpp v17, v17, v17 quad_perm:[2,3,0,1] row_mask:0xf bank_mask:0xf bound_ctrl:1
	ds_read_b128 v[94:97], v6 offset:16704
	v_add_f32_dpp v16, v16, v16 row_half_mirror row_mask:0xf bank_mask:0xf bound_ctrl:1
	v_add_f32_dpp v17, v17, v17 row_half_mirror row_mask:0xf bank_mask:0xf bound_ctrl:1
	s_nop 0
	v_add_f32_dpp v16, v16, v16 row_mirror row_mask:0xf bank_mask:0xf bound_ctrl:1
	v_add_f32_dpp v17, v17, v17 row_mirror row_mask:0xf bank_mask:0xf bound_ctrl:1
	v_pk_fma_f32 v[2:3], v[198:199], v[16:17], v[18:19] op_sel_hi:[1,0,1]
	v_pk_fma_f32 v[4:5], v[200:201], v[16:17], v[20:21] op_sel_hi:[1,0,1]
	s_waitcnt lgkmcnt(5)
	v_pk_mul_f32 v[10:11], v[2:3], v[58:59] op_sel_hi:[0,1]
	ds_read_b128 v[98:101], v6 offset:17920
	v_pk_mul_f32 v[18:19], v[74:75], v[118:119] op_sel_hi:[1,0]
	v_pk_fma_f32 v[10:11], v[2:3], v[60:61], v[10:11] op_sel:[1,0,0] op_sel_hi:[1,1,1]
	ds_read_b128 v[102:105], v6 offset:17936
	v_pk_mul_f32 v[20:21], v[76:77], v[118:119] op_sel_hi:[1,0]
	v_pk_fma_f32 v[10:11], v[4:5], v[62:63], v[10:11] op_sel_hi:[0,1,1]
	ds_read_b128 v[106:109], v6 offset:17952
	v_pk_fma_f32 v[18:19], v[2:3], v[66:67], v[18:19]
	v_pk_fma_f32 v[10:11], v[4:5], v[64:65], v[10:11] op_sel:[1,0,0] op_sel_hi:[1,1,1]
	v_pk_fma_f32 v[20:21], v[4:5], v[68:69], v[20:21]
	v_fmac_f32_e32 v17, v210, v16
	v_add_f32_dpp v10, v10, v10 quad_perm:[1,0,3,2] row_mask:0xf bank_mask:0xf bound_ctrl:1
	v_add_f32_dpp v11, v11, v11 quad_perm:[1,0,3,2] row_mask:0xf bank_mask:0xf bound_ctrl:1
	v_fmac_f32_e32 v17, v207, v211
	ds_write2_b32 v9, v15, v17 offset0:160 offset1:176
	v_add_f32_dpp v10, v10, v10 quad_perm:[2,3,0,1] row_mask:0xf bank_mask:0xf bound_ctrl:1
	v_add_f32_dpp v11, v11, v11 quad_perm:[2,3,0,1] row_mask:0xf bank_mask:0xf bound_ctrl:1
	ds_read_b128 v[110:113], v6 offset:17968
	v_add_f32_dpp v10, v10, v10 row_half_mirror row_mask:0xf bank_mask:0xf bound_ctrl:1
	v_add_f32_dpp v11, v11, v11 row_half_mirror row_mask:0xf bank_mask:0xf bound_ctrl:1
	ds_read_b128 v[114:117], v6 offset:17984
	v_add_f32_dpp v10, v10, v10 row_mirror row_mask:0xf bank_mask:0xf bound_ctrl:1
	v_add_f32_dpp v11, v11, v11 row_mirror row_mask:0xf bank_mask:0xf bound_ctrl:1
	v_pk_fma_f32 v[2:3], v[70:71], v[10:11], v[18:19] op_sel_hi:[1,0,1]
	v_pk_fma_f32 v[4:5], v[72:73], v[10:11], v[20:21] op_sel_hi:[1,0,1]
	ds_read2st64_b32 v[206:207], v7 offset0:14 offset1:15
	ds_read_b128 v[208:211], v8 offset:112
	s_waitcnt lgkmcnt(8)
	v_pk_mul_f32 v[12:13], v[2:3], v[78:79] op_sel_hi:[0,1]
	ds_read_b128 v[186:189], v6 offset:19200
	v_pk_mul_f32 v[18:19], v[94:95], v[118:119] op_sel:[0,1] op_sel_hi:[1,1]
	v_pk_fma_f32 v[12:13], v[2:3], v[80:81], v[12:13] op_sel:[1,0,0] op_sel_hi:[1,1,1]
	ds_read_b128 v[190:193], v6 offset:19216
	v_pk_mul_f32 v[20:21], v[96:97], v[118:119] op_sel:[0,1] op_sel_hi:[1,1]
	v_pk_fma_f32 v[12:13], v[4:5], v[82:83], v[12:13] op_sel_hi:[0,1,1]
	ds_read_b128 v[194:197], v6 offset:19232
	v_pk_fma_f32 v[18:19], v[2:3], v[86:87], v[18:19]
	v_pk_fma_f32 v[12:13], v[4:5], v[84:85], v[12:13] op_sel:[1,0,0] op_sel_hi:[1,1,1]
	v_pk_fma_f32 v[20:21], v[4:5], v[88:89], v[20:21]
	v_fmac_f32_e32 v11, v120, v10
	v_add_f32_dpp v12, v12, v12 quad_perm:[1,0,3,2] row_mask:0xf bank_mask:0xf bound_ctrl:1
	v_add_f32_dpp v13, v13, v13 quad_perm:[1,0,3,2] row_mask:0xf bank_mask:0xf bound_ctrl:1
	v_fmac_f32_e32 v11, v118, v121
	ds_read_b128 v[198:201], v6 offset:19248
	v_add_f32_dpp v12, v12, v12 quad_perm:[2,3,0,1] row_mask:0xf bank_mask:0xf bound_ctrl:1
	v_add_f32_dpp v13, v13, v13 quad_perm:[2,3,0,1] row_mask:0xf bank_mask:0xf bound_ctrl:1
	ds_read_b128 v[202:205], v6 offset:19264
	v_add_f32_dpp v12, v12, v12 row_half_mirror row_mask:0xf bank_mask:0xf bound_ctrl:1
	v_add_f32_dpp v13, v13, v13 row_half_mirror row_mask:0xf bank_mask:0xf bound_ctrl:1
	s_nop 0
	v_add_f32_dpp v12, v12, v12 row_mirror row_mask:0xf bank_mask:0xf bound_ctrl:1
	v_add_f32_dpp v13, v13, v13 row_mirror row_mask:0xf bank_mask:0xf bound_ctrl:1
	v_pk_fma_f32 v[2:3], v[90:91], v[12:13], v[18:19] op_sel_hi:[1,0,1]
	v_pk_fma_f32 v[4:5], v[92:93], v[12:13], v[20:21] op_sel_hi:[1,0,1]
	s_waitcnt lgkmcnt(5)
	v_pk_mul_f32 v[14:15], v[2:3], v[98:99] op_sel_hi:[0,1]
	ds_read_b128 v[58:61], v6 offset:20480
	v_pk_mul_f32 v[18:19], v[114:115], v[206:207] op_sel_hi:[1,0]
	v_pk_fma_f32 v[14:15], v[2:3], v[100:101], v[14:15] op_sel:[1,0,0] op_sel_hi:[1,1,1]
	ds_read_b128 v[62:65], v6 offset:20496
	v_pk_mul_f32 v[20:21], v[116:117], v[206:207] op_sel_hi:[1,0]
	v_pk_fma_f32 v[14:15], v[4:5], v[102:103], v[14:15] op_sel_hi:[0,1,1]
	ds_read_b128 v[66:69], v6 offset:20512
	v_pk_fma_f32 v[18:19], v[2:3], v[106:107], v[18:19]
	v_pk_fma_f32 v[14:15], v[4:5], v[104:105], v[14:15] op_sel:[1,0,0] op_sel_hi:[1,1,1]
	v_pk_fma_f32 v[20:21], v[4:5], v[108:109], v[20:21]
	v_fmac_f32_e32 v13, v122, v12
	v_add_f32_dpp v14, v14, v14 quad_perm:[1,0,3,2] row_mask:0xf bank_mask:0xf bound_ctrl:1
	v_add_f32_dpp v15, v15, v15 quad_perm:[1,0,3,2] row_mask:0xf bank_mask:0xf bound_ctrl:1
	v_fmac_f32_e32 v13, v119, v123
	ds_write2_b32 v9, v11, v13 offset0:192 offset1:208
	v_add_f32_dpp v14, v14, v14 quad_perm:[2,3,0,1] row_mask:0xf bank_mask:0xf bound_ctrl:1
	v_add_f32_dpp v15, v15, v15 quad_perm:[2,3,0,1] row_mask:0xf bank_mask:0xf bound_ctrl:1
	ds_read_b128 v[70:73], v6 offset:20528
	v_add_f32_dpp v14, v14, v14 row_half_mirror row_mask:0xf bank_mask:0xf bound_ctrl:1
	v_add_f32_dpp v15, v15, v15 row_half_mirror row_mask:0xf bank_mask:0xf bound_ctrl:1
	ds_read_b128 v[74:77], v6 offset:20544
	v_add_f32_dpp v14, v14, v14 row_mirror row_mask:0xf bank_mask:0xf bound_ctrl:1
	v_add_f32_dpp v15, v15, v15 row_mirror row_mask:0xf bank_mask:0xf bound_ctrl:1
	v_pk_fma_f32 v[2:3], v[110:111], v[14:15], v[18:19] op_sel_hi:[1,0,1]
	v_pk_fma_f32 v[4:5], v[112:113], v[14:15], v[20:21] op_sel_hi:[1,0,1]
	ds_read2st64_b32 v[118:119], v7 offset0:16 offset1:17
	ds_read_b128 v[120:123], v8 offset:128
	s_waitcnt lgkmcnt(8)
	v_pk_mul_f32 v[16:17], v[2:3], v[186:187] op_sel_hi:[0,1]
	ds_read_b128 v[78:81], v6 offset:21760
	v_pk_mul_f32 v[18:19], v[202:203], v[206:207] op_sel:[0,1] op_sel_hi:[1,1]
	v_pk_fma_f32 v[16:17], v[2:3], v[188:189], v[16:17] op_sel:[1,0,0] op_sel_hi:[1,1,1]
	ds_read_b128 v[82:85], v6 offset:21776
	v_pk_mul_f32 v[20:21], v[204:205], v[206:207] op_sel:[0,1] op_sel_hi:[1,1]
	v_pk_fma_f32 v[16:17], v[4:5], v[190:191], v[16:17] op_sel_hi:[0,1,1]
	ds_read_b128 v[86:89], v6 offset:21792
	v_pk_fma_f32 v[18:19], v[2:3], v[194:195], v[18:19]
	v_pk_fma_f32 v[16:17], v[4:5], v[192:193], v[16:17] op_sel:[1,0,0] op_sel_hi:[1,1,1]
	v_pk_fma_f32 v[20:21], v[4:5], v[196:197], v[20:21]
	v_fmac_f32_e32 v15, v208, v14
	v_add_f32_dpp v16, v16, v16 quad_perm:[1,0,3,2] row_mask:0xf bank_mask:0xf bound_ctrl:1
	v_add_f32_dpp v17, v17, v17 quad_perm:[1,0,3,2] row_mask:0xf bank_mask:0xf bound_ctrl:1
	v_fmac_f32_e32 v15, v206, v209
	ds_read_b128 v[90:93], v6 offset:21808
	v_add_f32_dpp v16, v16, v16 quad_perm:[2,3,0,1] row_mask:0xf bank_mask:0xf bound_ctrl:1
	v_add_f32_dpp v17, v17, v17 quad_perm:[2,3,0,1] row_mask:0xf bank_mask:0xf bound_ctrl:1
	ds_read_b128 v[94:97], v6 offset:21824
	v_add_f32_dpp v16, v16, v16 row_half_mirror row_mask:0xf bank_mask:0xf bound_ctrl:1
	v_add_f32_dpp v17, v17, v17 row_half_mirror row_mask:0xf bank_mask:0xf bound_ctrl:1
	s_nop 0
	v_add_f32_dpp v16, v16, v16 row_mirror row_mask:0xf bank_mask:0xf bound_ctrl:1
	v_add_f32_dpp v17, v17, v17 row_mirror row_mask:0xf bank_mask:0xf bound_ctrl:1
	v_pk_fma_f32 v[2:3], v[198:199], v[16:17], v[18:19] op_sel_hi:[1,0,1]
	v_pk_fma_f32 v[4:5], v[200:201], v[16:17], v[20:21] op_sel_hi:[1,0,1]
	s_waitcnt lgkmcnt(5)
	v_pk_mul_f32 v[10:11], v[2:3], v[58:59] op_sel_hi:[0,1]
	ds_read_b128 v[98:101], v6 offset:23040
	v_pk_mul_f32 v[18:19], v[74:75], v[118:119] op_sel_hi:[1,0]
	v_pk_fma_f32 v[10:11], v[2:3], v[60:61], v[10:11] op_sel:[1,0,0] op_sel_hi:[1,1,1]
	ds_read_b128 v[102:105], v6 offset:23056
	v_pk_mul_f32 v[20:21], v[76:77], v[118:119] op_sel_hi:[1,0]
	v_pk_fma_f32 v[10:11], v[4:5], v[62:63], v[10:11] op_sel_hi:[0,1,1]
	ds_read_b128 v[106:109], v6 offset:23072
	v_pk_fma_f32 v[18:19], v[2:3], v[66:67], v[18:19]
	v_pk_fma_f32 v[10:11], v[4:5], v[64:65], v[10:11] op_sel:[1,0,0] op_sel_hi:[1,1,1]
	v_pk_fma_f32 v[20:21], v[4:5], v[68:69], v[20:21]
	v_fmac_f32_e32 v17, v210, v16
	v_add_f32_dpp v10, v10, v10 quad_perm:[1,0,3,2] row_mask:0xf bank_mask:0xf bound_ctrl:1
	v_add_f32_dpp v11, v11, v11 quad_perm:[1,0,3,2] row_mask:0xf bank_mask:0xf bound_ctrl:1
	v_fmac_f32_e32 v17, v207, v211
	ds_write2_b32 v9, v15, v17 offset0:224 offset1:240
	v_add_f32_dpp v10, v10, v10 quad_perm:[2,3,0,1] row_mask:0xf bank_mask:0xf bound_ctrl:1
	v_add_f32_dpp v11, v11, v11 quad_perm:[2,3,0,1] row_mask:0xf bank_mask:0xf bound_ctrl:1
	ds_read_b128 v[110:113], v6 offset:23088
	v_add_f32_dpp v10, v10, v10 row_half_mirror row_mask:0xf bank_mask:0xf bound_ctrl:1
	v_add_f32_dpp v11, v11, v11 row_half_mirror row_mask:0xf bank_mask:0xf bound_ctrl:1
	ds_read_b128 v[114:117], v6 offset:23104
	v_add_f32_dpp v10, v10, v10 row_mirror row_mask:0xf bank_mask:0xf bound_ctrl:1
	v_add_f32_dpp v11, v11, v11 row_mirror row_mask:0xf bank_mask:0xf bound_ctrl:1
	v_pk_fma_f32 v[2:3], v[70:71], v[10:11], v[18:19] op_sel_hi:[1,0,1]
	v_pk_fma_f32 v[4:5], v[72:73], v[10:11], v[20:21] op_sel_hi:[1,0,1]
	ds_read2st64_b32 v[206:207], v7 offset0:18 offset1:19
	ds_read_b128 v[208:211], v8 offset:144
	s_waitcnt lgkmcnt(8)
	v_pk_mul_f32 v[12:13], v[2:3], v[78:79] op_sel_hi:[0,1]
	ds_read_b128 v[186:189], v6 offset:24320
	v_pk_mul_f32 v[18:19], v[94:95], v[118:119] op_sel:[0,1] op_sel_hi:[1,1]
	v_pk_fma_f32 v[12:13], v[2:3], v[80:81], v[12:13] op_sel:[1,0,0] op_sel_hi:[1,1,1]
	ds_read_b128 v[190:193], v6 offset:24336
	v_pk_mul_f32 v[20:21], v[96:97], v[118:119] op_sel:[0,1] op_sel_hi:[1,1]
	v_pk_fma_f32 v[12:13], v[4:5], v[82:83], v[12:13] op_sel_hi:[0,1,1]
	ds_read_b128 v[194:197], v6 offset:24352
	v_pk_fma_f32 v[18:19], v[2:3], v[86:87], v[18:19]
	v_pk_fma_f32 v[12:13], v[4:5], v[84:85], v[12:13] op_sel:[1,0,0] op_sel_hi:[1,1,1]
	v_pk_fma_f32 v[20:21], v[4:5], v[88:89], v[20:21]
	v_fmac_f32_e32 v11, v120, v10
	v_add_f32_dpp v12, v12, v12 quad_perm:[1,0,3,2] row_mask:0xf bank_mask:0xf bound_ctrl:1
	v_add_f32_dpp v13, v13, v13 quad_perm:[1,0,3,2] row_mask:0xf bank_mask:0xf bound_ctrl:1
	v_fmac_f32_e32 v11, v118, v121
	ds_read_b128 v[198:201], v6 offset:24368
	v_add_f32_dpp v12, v12, v12 quad_perm:[2,3,0,1] row_mask:0xf bank_mask:0xf bound_ctrl:1
	v_add_f32_dpp v13, v13, v13 quad_perm:[2,3,0,1] row_mask:0xf bank_mask:0xf bound_ctrl:1
	ds_read_b128 v[202:205], v6 offset:24384
	v_add_f32_dpp v12, v12, v12 row_half_mirror row_mask:0xf bank_mask:0xf bound_ctrl:1
	v_add_f32_dpp v13, v13, v13 row_half_mirror row_mask:0xf bank_mask:0xf bound_ctrl:1
	s_nop 0
	v_add_f32_dpp v12, v12, v12 row_mirror row_mask:0xf bank_mask:0xf bound_ctrl:1
	v_add_f32_dpp v13, v13, v13 row_mirror row_mask:0xf bank_mask:0xf bound_ctrl:1
	v_pk_fma_f32 v[2:3], v[90:91], v[12:13], v[18:19] op_sel_hi:[1,0,1]
	v_pk_fma_f32 v[4:5], v[92:93], v[12:13], v[20:21] op_sel_hi:[1,0,1]
	s_waitcnt lgkmcnt(5)
	v_pk_mul_f32 v[14:15], v[2:3], v[98:99] op_sel_hi:[0,1]
	ds_read_b128 v[58:61], v6 offset:25600
	v_pk_mul_f32 v[18:19], v[114:115], v[206:207] op_sel_hi:[1,0]
	v_pk_fma_f32 v[14:15], v[2:3], v[100:101], v[14:15] op_sel:[1,0,0] op_sel_hi:[1,1,1]
	ds_read_b128 v[62:65], v6 offset:25616
	v_pk_mul_f32 v[20:21], v[116:117], v[206:207] op_sel_hi:[1,0]
	v_pk_fma_f32 v[14:15], v[4:5], v[102:103], v[14:15] op_sel_hi:[0,1,1]
	ds_read_b128 v[66:69], v6 offset:25632
	v_pk_fma_f32 v[18:19], v[2:3], v[106:107], v[18:19]
	v_pk_fma_f32 v[14:15], v[4:5], v[104:105], v[14:15] op_sel:[1,0,0] op_sel_hi:[1,1,1]
	v_pk_fma_f32 v[20:21], v[4:5], v[108:109], v[20:21]
	v_fmac_f32_e32 v13, v122, v12
	v_add_f32_dpp v14, v14, v14 quad_perm:[1,0,3,2] row_mask:0xf bank_mask:0xf bound_ctrl:1
	v_add_f32_dpp v15, v15, v15 quad_perm:[1,0,3,2] row_mask:0xf bank_mask:0xf bound_ctrl:1
	v_fmac_f32_e32 v13, v119, v123
	ds_write2_b32 v22, v11, v13 offset1:16
	v_add_f32_dpp v14, v14, v14 quad_perm:[2,3,0,1] row_mask:0xf bank_mask:0xf bound_ctrl:1
	v_add_f32_dpp v15, v15, v15 quad_perm:[2,3,0,1] row_mask:0xf bank_mask:0xf bound_ctrl:1
	ds_read_b128 v[70:73], v6 offset:25648
	v_add_f32_dpp v14, v14, v14 row_half_mirror row_mask:0xf bank_mask:0xf bound_ctrl:1
	v_add_f32_dpp v15, v15, v15 row_half_mirror row_mask:0xf bank_mask:0xf bound_ctrl:1
	ds_read_b128 v[74:77], v6 offset:25664
	v_add_f32_dpp v14, v14, v14 row_mirror row_mask:0xf bank_mask:0xf bound_ctrl:1
	v_add_f32_dpp v15, v15, v15 row_mirror row_mask:0xf bank_mask:0xf bound_ctrl:1
	v_pk_fma_f32 v[2:3], v[110:111], v[14:15], v[18:19] op_sel_hi:[1,0,1]
	v_pk_fma_f32 v[4:5], v[112:113], v[14:15], v[20:21] op_sel_hi:[1,0,1]
	ds_read2st64_b32 v[118:119], v7 offset0:20 offset1:21
	ds_read_b128 v[120:123], v8 offset:160
	s_waitcnt lgkmcnt(8)
	v_pk_mul_f32 v[16:17], v[2:3], v[186:187] op_sel_hi:[0,1]
	ds_read_b128 v[78:81], v6 offset:26880
	v_pk_mul_f32 v[18:19], v[202:203], v[206:207] op_sel:[0,1] op_sel_hi:[1,1]
	v_pk_fma_f32 v[16:17], v[2:3], v[188:189], v[16:17] op_sel:[1,0,0] op_sel_hi:[1,1,1]
	ds_read_b128 v[82:85], v6 offset:26896
	v_pk_mul_f32 v[20:21], v[204:205], v[206:207] op_sel:[0,1] op_sel_hi:[1,1]
	v_pk_fma_f32 v[16:17], v[4:5], v[190:191], v[16:17] op_sel_hi:[0,1,1]
	ds_read_b128 v[86:89], v6 offset:26912
	v_pk_fma_f32 v[18:19], v[2:3], v[194:195], v[18:19]
	v_pk_fma_f32 v[16:17], v[4:5], v[192:193], v[16:17] op_sel:[1,0,0] op_sel_hi:[1,1,1]
	v_pk_fma_f32 v[20:21], v[4:5], v[196:197], v[20:21]
	v_fmac_f32_e32 v15, v208, v14
	v_add_f32_dpp v16, v16, v16 quad_perm:[1,0,3,2] row_mask:0xf bank_mask:0xf bound_ctrl:1
	v_add_f32_dpp v17, v17, v17 quad_perm:[1,0,3,2] row_mask:0xf bank_mask:0xf bound_ctrl:1
	v_fmac_f32_e32 v15, v206, v209
	ds_read_b128 v[90:93], v6 offset:26928
	v_add_f32_dpp v16, v16, v16 quad_perm:[2,3,0,1] row_mask:0xf bank_mask:0xf bound_ctrl:1
	v_add_f32_dpp v17, v17, v17 quad_perm:[2,3,0,1] row_mask:0xf bank_mask:0xf bound_ctrl:1
	ds_read_b128 v[94:97], v6 offset:26944
	v_add_f32_dpp v16, v16, v16 row_half_mirror row_mask:0xf bank_mask:0xf bound_ctrl:1
	v_add_f32_dpp v17, v17, v17 row_half_mirror row_mask:0xf bank_mask:0xf bound_ctrl:1
	s_nop 0
	v_add_f32_dpp v16, v16, v16 row_mirror row_mask:0xf bank_mask:0xf bound_ctrl:1
	v_add_f32_dpp v17, v17, v17 row_mirror row_mask:0xf bank_mask:0xf bound_ctrl:1
	v_pk_fma_f32 v[2:3], v[198:199], v[16:17], v[18:19] op_sel_hi:[1,0,1]
	v_pk_fma_f32 v[4:5], v[200:201], v[16:17], v[20:21] op_sel_hi:[1,0,1]
	s_waitcnt lgkmcnt(5)
	v_pk_mul_f32 v[10:11], v[2:3], v[58:59] op_sel_hi:[0,1]
	ds_read_b128 v[98:101], v6 offset:28160
	v_pk_mul_f32 v[18:19], v[74:75], v[118:119] op_sel_hi:[1,0]
	v_pk_fma_f32 v[10:11], v[2:3], v[60:61], v[10:11] op_sel:[1,0,0] op_sel_hi:[1,1,1]
	ds_read_b128 v[102:105], v6 offset:28176
	v_pk_mul_f32 v[20:21], v[76:77], v[118:119] op_sel_hi:[1,0]
	v_pk_fma_f32 v[10:11], v[4:5], v[62:63], v[10:11] op_sel_hi:[0,1,1]
	ds_read_b128 v[106:109], v6 offset:28192
	v_pk_fma_f32 v[18:19], v[2:3], v[66:67], v[18:19]
	v_pk_fma_f32 v[10:11], v[4:5], v[64:65], v[10:11] op_sel:[1,0,0] op_sel_hi:[1,1,1]
	v_pk_fma_f32 v[20:21], v[4:5], v[68:69], v[20:21]
	v_fmac_f32_e32 v17, v210, v16
	v_add_f32_dpp v10, v10, v10 quad_perm:[1,0,3,2] row_mask:0xf bank_mask:0xf bound_ctrl:1
	v_add_f32_dpp v11, v11, v11 quad_perm:[1,0,3,2] row_mask:0xf bank_mask:0xf bound_ctrl:1
	v_fmac_f32_e32 v17, v207, v211
	ds_write2_b32 v22, v15, v17 offset0:32 offset1:48
	v_add_f32_dpp v10, v10, v10 quad_perm:[2,3,0,1] row_mask:0xf bank_mask:0xf bound_ctrl:1
	v_add_f32_dpp v11, v11, v11 quad_perm:[2,3,0,1] row_mask:0xf bank_mask:0xf bound_ctrl:1
	ds_read_b128 v[110:113], v6 offset:28208
	v_add_f32_dpp v10, v10, v10 row_half_mirror row_mask:0xf bank_mask:0xf bound_ctrl:1
	v_add_f32_dpp v11, v11, v11 row_half_mirror row_mask:0xf bank_mask:0xf bound_ctrl:1
	ds_read_b128 v[114:117], v6 offset:28224
	v_add_f32_dpp v10, v10, v10 row_mirror row_mask:0xf bank_mask:0xf bound_ctrl:1
	v_add_f32_dpp v11, v11, v11 row_mirror row_mask:0xf bank_mask:0xf bound_ctrl:1
	v_pk_fma_f32 v[2:3], v[70:71], v[10:11], v[18:19] op_sel_hi:[1,0,1]
	v_pk_fma_f32 v[4:5], v[72:73], v[10:11], v[20:21] op_sel_hi:[1,0,1]
	ds_read2st64_b32 v[206:207], v7 offset0:22 offset1:23
	ds_read_b128 v[208:211], v8 offset:176
	s_waitcnt lgkmcnt(8)
	v_pk_mul_f32 v[12:13], v[2:3], v[78:79] op_sel_hi:[0,1]
	ds_read_b128 v[186:189], v6 offset:29440
	v_pk_mul_f32 v[18:19], v[94:95], v[118:119] op_sel:[0,1] op_sel_hi:[1,1]
	v_pk_fma_f32 v[12:13], v[2:3], v[80:81], v[12:13] op_sel:[1,0,0] op_sel_hi:[1,1,1]
	ds_read_b128 v[190:193], v6 offset:29456
	v_pk_mul_f32 v[20:21], v[96:97], v[118:119] op_sel:[0,1] op_sel_hi:[1,1]
	v_pk_fma_f32 v[12:13], v[4:5], v[82:83], v[12:13] op_sel_hi:[0,1,1]
	ds_read_b128 v[194:197], v6 offset:29472
	v_pk_fma_f32 v[18:19], v[2:3], v[86:87], v[18:19]
	v_pk_fma_f32 v[12:13], v[4:5], v[84:85], v[12:13] op_sel:[1,0,0] op_sel_hi:[1,1,1]
	v_pk_fma_f32 v[20:21], v[4:5], v[88:89], v[20:21]
	v_fmac_f32_e32 v11, v120, v10
	v_add_f32_dpp v12, v12, v12 quad_perm:[1,0,3,2] row_mask:0xf bank_mask:0xf bound_ctrl:1
	v_add_f32_dpp v13, v13, v13 quad_perm:[1,0,3,2] row_mask:0xf bank_mask:0xf bound_ctrl:1
	v_fmac_f32_e32 v11, v118, v121
	ds_read_b128 v[198:201], v6 offset:29488
	v_add_f32_dpp v12, v12, v12 quad_perm:[2,3,0,1] row_mask:0xf bank_mask:0xf bound_ctrl:1
	v_add_f32_dpp v13, v13, v13 quad_perm:[2,3,0,1] row_mask:0xf bank_mask:0xf bound_ctrl:1
	ds_read_b128 v[202:205], v6 offset:29504
	v_add_f32_dpp v12, v12, v12 row_half_mirror row_mask:0xf bank_mask:0xf bound_ctrl:1
	v_add_f32_dpp v13, v13, v13 row_half_mirror row_mask:0xf bank_mask:0xf bound_ctrl:1
	s_nop 0
	v_add_f32_dpp v12, v12, v12 row_mirror row_mask:0xf bank_mask:0xf bound_ctrl:1
	v_add_f32_dpp v13, v13, v13 row_mirror row_mask:0xf bank_mask:0xf bound_ctrl:1
	v_pk_fma_f32 v[2:3], v[90:91], v[12:13], v[18:19] op_sel_hi:[1,0,1]
	v_pk_fma_f32 v[4:5], v[92:93], v[12:13], v[20:21] op_sel_hi:[1,0,1]
	s_waitcnt lgkmcnt(5)
	v_pk_mul_f32 v[14:15], v[2:3], v[98:99] op_sel_hi:[0,1]
	ds_read_b128 v[58:61], v6 offset:30720
	v_pk_mul_f32 v[18:19], v[114:115], v[206:207] op_sel_hi:[1,0]
	v_pk_fma_f32 v[14:15], v[2:3], v[100:101], v[14:15] op_sel:[1,0,0] op_sel_hi:[1,1,1]
	ds_read_b128 v[62:65], v6 offset:30736
	v_pk_mul_f32 v[20:21], v[116:117], v[206:207] op_sel_hi:[1,0]
	v_pk_fma_f32 v[14:15], v[4:5], v[102:103], v[14:15] op_sel_hi:[0,1,1]
	ds_read_b128 v[66:69], v6 offset:30752
	v_pk_fma_f32 v[18:19], v[2:3], v[106:107], v[18:19]
	v_pk_fma_f32 v[14:15], v[4:5], v[104:105], v[14:15] op_sel:[1,0,0] op_sel_hi:[1,1,1]
	v_pk_fma_f32 v[20:21], v[4:5], v[108:109], v[20:21]
	v_fmac_f32_e32 v13, v122, v12
	v_add_f32_dpp v14, v14, v14 quad_perm:[1,0,3,2] row_mask:0xf bank_mask:0xf bound_ctrl:1
	v_add_f32_dpp v15, v15, v15 quad_perm:[1,0,3,2] row_mask:0xf bank_mask:0xf bound_ctrl:1
	v_fmac_f32_e32 v13, v119, v123
	ds_write2_b32 v22, v11, v13 offset0:64 offset1:80
	v_add_f32_dpp v14, v14, v14 quad_perm:[2,3,0,1] row_mask:0xf bank_mask:0xf bound_ctrl:1
	v_add_f32_dpp v15, v15, v15 quad_perm:[2,3,0,1] row_mask:0xf bank_mask:0xf bound_ctrl:1
	ds_read_b128 v[70:73], v6 offset:30768
	v_add_f32_dpp v14, v14, v14 row_half_mirror row_mask:0xf bank_mask:0xf bound_ctrl:1
	v_add_f32_dpp v15, v15, v15 row_half_mirror row_mask:0xf bank_mask:0xf bound_ctrl:1
	ds_read_b128 v[74:77], v6 offset:30784
	v_add_f32_dpp v14, v14, v14 row_mirror row_mask:0xf bank_mask:0xf bound_ctrl:1
	v_add_f32_dpp v15, v15, v15 row_mirror row_mask:0xf bank_mask:0xf bound_ctrl:1
	v_pk_fma_f32 v[2:3], v[110:111], v[14:15], v[18:19] op_sel_hi:[1,0,1]
	v_pk_fma_f32 v[4:5], v[112:113], v[14:15], v[20:21] op_sel_hi:[1,0,1]
	ds_read2st64_b32 v[118:119], v7 offset0:24 offset1:25
	ds_read_b128 v[120:123], v8 offset:192
	s_waitcnt lgkmcnt(8)
	v_pk_mul_f32 v[16:17], v[2:3], v[186:187] op_sel_hi:[0,1]
	ds_read_b128 v[78:81], v6 offset:32000
	v_pk_mul_f32 v[18:19], v[202:203], v[206:207] op_sel:[0,1] op_sel_hi:[1,1]
	v_pk_fma_f32 v[16:17], v[2:3], v[188:189], v[16:17] op_sel:[1,0,0] op_sel_hi:[1,1,1]
	ds_read_b128 v[82:85], v6 offset:32016
	v_pk_mul_f32 v[20:21], v[204:205], v[206:207] op_sel:[0,1] op_sel_hi:[1,1]
	v_pk_fma_f32 v[16:17], v[4:5], v[190:191], v[16:17] op_sel_hi:[0,1,1]
	ds_read_b128 v[86:89], v6 offset:32032
	v_pk_fma_f32 v[18:19], v[2:3], v[194:195], v[18:19]
	v_pk_fma_f32 v[16:17], v[4:5], v[192:193], v[16:17] op_sel:[1,0,0] op_sel_hi:[1,1,1]
	v_pk_fma_f32 v[20:21], v[4:5], v[196:197], v[20:21]
	v_fmac_f32_e32 v15, v208, v14
	v_add_f32_dpp v16, v16, v16 quad_perm:[1,0,3,2] row_mask:0xf bank_mask:0xf bound_ctrl:1
	v_add_f32_dpp v17, v17, v17 quad_perm:[1,0,3,2] row_mask:0xf bank_mask:0xf bound_ctrl:1
	v_fmac_f32_e32 v15, v206, v209
	ds_read_b128 v[90:93], v6 offset:32048
	v_add_f32_dpp v16, v16, v16 quad_perm:[2,3,0,1] row_mask:0xf bank_mask:0xf bound_ctrl:1
	v_add_f32_dpp v17, v17, v17 quad_perm:[2,3,0,1] row_mask:0xf bank_mask:0xf bound_ctrl:1
	ds_read_b128 v[94:97], v6 offset:32064
	v_add_f32_dpp v16, v16, v16 row_half_mirror row_mask:0xf bank_mask:0xf bound_ctrl:1
	v_add_f32_dpp v17, v17, v17 row_half_mirror row_mask:0xf bank_mask:0xf bound_ctrl:1
	s_nop 0
	v_add_f32_dpp v16, v16, v16 row_mirror row_mask:0xf bank_mask:0xf bound_ctrl:1
	v_add_f32_dpp v17, v17, v17 row_mirror row_mask:0xf bank_mask:0xf bound_ctrl:1
	v_pk_fma_f32 v[2:3], v[198:199], v[16:17], v[18:19] op_sel_hi:[1,0,1]
	v_pk_fma_f32 v[4:5], v[200:201], v[16:17], v[20:21] op_sel_hi:[1,0,1]
	s_waitcnt lgkmcnt(5)
	v_pk_mul_f32 v[10:11], v[2:3], v[58:59] op_sel_hi:[0,1]
	ds_read_b128 v[98:101], v6 offset:33280
	v_pk_mul_f32 v[18:19], v[74:75], v[118:119] op_sel_hi:[1,0]
	v_pk_fma_f32 v[10:11], v[2:3], v[60:61], v[10:11] op_sel:[1,0,0] op_sel_hi:[1,1,1]
	ds_read_b128 v[102:105], v6 offset:33296
	v_pk_mul_f32 v[20:21], v[76:77], v[118:119] op_sel_hi:[1,0]
	v_pk_fma_f32 v[10:11], v[4:5], v[62:63], v[10:11] op_sel_hi:[0,1,1]
	ds_read_b128 v[106:109], v6 offset:33312
	v_pk_fma_f32 v[18:19], v[2:3], v[66:67], v[18:19]
	v_pk_fma_f32 v[10:11], v[4:5], v[64:65], v[10:11] op_sel:[1,0,0] op_sel_hi:[1,1,1]
	v_pk_fma_f32 v[20:21], v[4:5], v[68:69], v[20:21]
	v_fmac_f32_e32 v17, v210, v16
	v_add_f32_dpp v10, v10, v10 quad_perm:[1,0,3,2] row_mask:0xf bank_mask:0xf bound_ctrl:1
	v_add_f32_dpp v11, v11, v11 quad_perm:[1,0,3,2] row_mask:0xf bank_mask:0xf bound_ctrl:1
	v_fmac_f32_e32 v17, v207, v211
	ds_write2_b32 v22, v15, v17 offset0:96 offset1:112
	v_add_f32_dpp v10, v10, v10 quad_perm:[2,3,0,1] row_mask:0xf bank_mask:0xf bound_ctrl:1
	v_add_f32_dpp v11, v11, v11 quad_perm:[2,3,0,1] row_mask:0xf bank_mask:0xf bound_ctrl:1
	ds_read_b128 v[110:113], v6 offset:33328
	v_add_f32_dpp v10, v10, v10 row_half_mirror row_mask:0xf bank_mask:0xf bound_ctrl:1
	v_add_f32_dpp v11, v11, v11 row_half_mirror row_mask:0xf bank_mask:0xf bound_ctrl:1
	ds_read_b128 v[114:117], v6 offset:33344
	v_add_f32_dpp v10, v10, v10 row_mirror row_mask:0xf bank_mask:0xf bound_ctrl:1
	v_add_f32_dpp v11, v11, v11 row_mirror row_mask:0xf bank_mask:0xf bound_ctrl:1
	v_pk_fma_f32 v[2:3], v[70:71], v[10:11], v[18:19] op_sel_hi:[1,0,1]
	v_pk_fma_f32 v[4:5], v[72:73], v[10:11], v[20:21] op_sel_hi:[1,0,1]
	ds_read2st64_b32 v[206:207], v7 offset0:26 offset1:27
	ds_read_b128 v[208:211], v8 offset:208
	s_waitcnt lgkmcnt(8)
	v_pk_mul_f32 v[12:13], v[2:3], v[78:79] op_sel_hi:[0,1]
	ds_read_b128 v[186:189], v6 offset:34560
	v_pk_mul_f32 v[18:19], v[94:95], v[118:119] op_sel:[0,1] op_sel_hi:[1,1]
	v_pk_fma_f32 v[12:13], v[2:3], v[80:81], v[12:13] op_sel:[1,0,0] op_sel_hi:[1,1,1]
	ds_read_b128 v[190:193], v6 offset:34576
	v_pk_mul_f32 v[20:21], v[96:97], v[118:119] op_sel:[0,1] op_sel_hi:[1,1]
	v_pk_fma_f32 v[12:13], v[4:5], v[82:83], v[12:13] op_sel_hi:[0,1,1]
	ds_read_b128 v[194:197], v6 offset:34592
	v_pk_fma_f32 v[18:19], v[2:3], v[86:87], v[18:19]
	v_pk_fma_f32 v[12:13], v[4:5], v[84:85], v[12:13] op_sel:[1,0,0] op_sel_hi:[1,1,1]
	v_pk_fma_f32 v[20:21], v[4:5], v[88:89], v[20:21]
	v_fmac_f32_e32 v11, v120, v10
	v_add_f32_dpp v12, v12, v12 quad_perm:[1,0,3,2] row_mask:0xf bank_mask:0xf bound_ctrl:1
	v_add_f32_dpp v13, v13, v13 quad_perm:[1,0,3,2] row_mask:0xf bank_mask:0xf bound_ctrl:1
	v_fmac_f32_e32 v11, v118, v121
	ds_read_b128 v[198:201], v6 offset:34608
	v_add_f32_dpp v12, v12, v12 quad_perm:[2,3,0,1] row_mask:0xf bank_mask:0xf bound_ctrl:1
	v_add_f32_dpp v13, v13, v13 quad_perm:[2,3,0,1] row_mask:0xf bank_mask:0xf bound_ctrl:1
	ds_read_b128 v[202:205], v6 offset:34624
	v_add_f32_dpp v12, v12, v12 row_half_mirror row_mask:0xf bank_mask:0xf bound_ctrl:1
	v_add_f32_dpp v13, v13, v13 row_half_mirror row_mask:0xf bank_mask:0xf bound_ctrl:1
	s_nop 0
	v_add_f32_dpp v12, v12, v12 row_mirror row_mask:0xf bank_mask:0xf bound_ctrl:1
	v_add_f32_dpp v13, v13, v13 row_mirror row_mask:0xf bank_mask:0xf bound_ctrl:1
	v_pk_fma_f32 v[2:3], v[90:91], v[12:13], v[18:19] op_sel_hi:[1,0,1]
	v_pk_fma_f32 v[4:5], v[92:93], v[12:13], v[20:21] op_sel_hi:[1,0,1]
	s_waitcnt lgkmcnt(5)
	v_pk_mul_f32 v[14:15], v[2:3], v[98:99] op_sel_hi:[0,1]
	ds_read_b128 v[58:61], v6 offset:35840
	v_pk_mul_f32 v[18:19], v[114:115], v[206:207] op_sel_hi:[1,0]
	v_pk_fma_f32 v[14:15], v[2:3], v[100:101], v[14:15] op_sel:[1,0,0] op_sel_hi:[1,1,1]
	ds_read_b128 v[62:65], v6 offset:35856
	v_pk_mul_f32 v[20:21], v[116:117], v[206:207] op_sel_hi:[1,0]
	v_pk_fma_f32 v[14:15], v[4:5], v[102:103], v[14:15] op_sel_hi:[0,1,1]
	ds_read_b128 v[66:69], v6 offset:35872
	v_pk_fma_f32 v[18:19], v[2:3], v[106:107], v[18:19]
	v_pk_fma_f32 v[14:15], v[4:5], v[104:105], v[14:15] op_sel:[1,0,0] op_sel_hi:[1,1,1]
	v_pk_fma_f32 v[20:21], v[4:5], v[108:109], v[20:21]
	v_fmac_f32_e32 v13, v122, v12
	v_add_f32_dpp v14, v14, v14 quad_perm:[1,0,3,2] row_mask:0xf bank_mask:0xf bound_ctrl:1
	v_add_f32_dpp v15, v15, v15 quad_perm:[1,0,3,2] row_mask:0xf bank_mask:0xf bound_ctrl:1
	v_fmac_f32_e32 v13, v119, v123
	ds_write2_b32 v22, v11, v13 offset0:128 offset1:144
	v_add_f32_dpp v14, v14, v14 quad_perm:[2,3,0,1] row_mask:0xf bank_mask:0xf bound_ctrl:1
	v_add_f32_dpp v15, v15, v15 quad_perm:[2,3,0,1] row_mask:0xf bank_mask:0xf bound_ctrl:1
	ds_read_b128 v[70:73], v6 offset:35888
	v_add_f32_dpp v14, v14, v14 row_half_mirror row_mask:0xf bank_mask:0xf bound_ctrl:1
	v_add_f32_dpp v15, v15, v15 row_half_mirror row_mask:0xf bank_mask:0xf bound_ctrl:1
	ds_read_b128 v[74:77], v6 offset:35904
	v_add_f32_dpp v14, v14, v14 row_mirror row_mask:0xf bank_mask:0xf bound_ctrl:1
	v_add_f32_dpp v15, v15, v15 row_mirror row_mask:0xf bank_mask:0xf bound_ctrl:1
	v_pk_fma_f32 v[2:3], v[110:111], v[14:15], v[18:19] op_sel_hi:[1,0,1]
	v_pk_fma_f32 v[4:5], v[112:113], v[14:15], v[20:21] op_sel_hi:[1,0,1]
	ds_read2st64_b32 v[118:119], v7 offset0:28 offset1:29
	ds_read_b128 v[120:123], v8 offset:224
	s_waitcnt lgkmcnt(8)
	v_pk_mul_f32 v[16:17], v[2:3], v[186:187] op_sel_hi:[0,1]
	ds_read_b128 v[78:81], v6 offset:37120
	v_pk_mul_f32 v[18:19], v[202:203], v[206:207] op_sel:[0,1] op_sel_hi:[1,1]
	v_pk_fma_f32 v[16:17], v[2:3], v[188:189], v[16:17] op_sel:[1,0,0] op_sel_hi:[1,1,1]
	ds_read_b128 v[82:85], v6 offset:37136
	v_pk_mul_f32 v[20:21], v[204:205], v[206:207] op_sel:[0,1] op_sel_hi:[1,1]
	v_pk_fma_f32 v[16:17], v[4:5], v[190:191], v[16:17] op_sel_hi:[0,1,1]
	ds_read_b128 v[86:89], v6 offset:37152
	v_pk_fma_f32 v[18:19], v[2:3], v[194:195], v[18:19]
	v_pk_fma_f32 v[16:17], v[4:5], v[192:193], v[16:17] op_sel:[1,0,0] op_sel_hi:[1,1,1]
	v_pk_fma_f32 v[20:21], v[4:5], v[196:197], v[20:21]
	v_fmac_f32_e32 v15, v208, v14
	v_add_f32_dpp v16, v16, v16 quad_perm:[1,0,3,2] row_mask:0xf bank_mask:0xf bound_ctrl:1
	v_add_f32_dpp v17, v17, v17 quad_perm:[1,0,3,2] row_mask:0xf bank_mask:0xf bound_ctrl:1
	v_fmac_f32_e32 v15, v206, v209
	ds_read_b128 v[90:93], v6 offset:37168
	v_add_f32_dpp v16, v16, v16 quad_perm:[2,3,0,1] row_mask:0xf bank_mask:0xf bound_ctrl:1
	v_add_f32_dpp v17, v17, v17 quad_perm:[2,3,0,1] row_mask:0xf bank_mask:0xf bound_ctrl:1
	ds_read_b128 v[94:97], v6 offset:37184
	v_add_f32_dpp v16, v16, v16 row_half_mirror row_mask:0xf bank_mask:0xf bound_ctrl:1
	v_add_f32_dpp v17, v17, v17 row_half_mirror row_mask:0xf bank_mask:0xf bound_ctrl:1
	s_nop 0
	v_add_f32_dpp v16, v16, v16 row_mirror row_mask:0xf bank_mask:0xf bound_ctrl:1
	v_add_f32_dpp v17, v17, v17 row_mirror row_mask:0xf bank_mask:0xf bound_ctrl:1
	v_pk_fma_f32 v[2:3], v[198:199], v[16:17], v[18:19] op_sel_hi:[1,0,1]
	v_pk_fma_f32 v[4:5], v[200:201], v[16:17], v[20:21] op_sel_hi:[1,0,1]
	s_waitcnt lgkmcnt(5)
	v_pk_mul_f32 v[10:11], v[2:3], v[58:59] op_sel_hi:[0,1]
	ds_read_b128 v[98:101], v6 offset:38400
	v_pk_mul_f32 v[18:19], v[74:75], v[118:119] op_sel_hi:[1,0]
	v_pk_fma_f32 v[10:11], v[2:3], v[60:61], v[10:11] op_sel:[1,0,0] op_sel_hi:[1,1,1]
	ds_read_b128 v[102:105], v6 offset:38416
	v_pk_mul_f32 v[20:21], v[76:77], v[118:119] op_sel_hi:[1,0]
	v_pk_fma_f32 v[10:11], v[4:5], v[62:63], v[10:11] op_sel_hi:[0,1,1]
	ds_read_b128 v[106:109], v6 offset:38432
	v_pk_fma_f32 v[18:19], v[2:3], v[66:67], v[18:19]
	v_pk_fma_f32 v[10:11], v[4:5], v[64:65], v[10:11] op_sel:[1,0,0] op_sel_hi:[1,1,1]
	v_pk_fma_f32 v[20:21], v[4:5], v[68:69], v[20:21]
	v_fmac_f32_e32 v17, v210, v16
	v_add_f32_dpp v10, v10, v10 quad_perm:[1,0,3,2] row_mask:0xf bank_mask:0xf bound_ctrl:1
	v_add_f32_dpp v11, v11, v11 quad_perm:[1,0,3,2] row_mask:0xf bank_mask:0xf bound_ctrl:1
	v_fmac_f32_e32 v17, v207, v211
	ds_write2_b32 v22, v15, v17 offset0:160 offset1:176
	v_add_f32_dpp v10, v10, v10 quad_perm:[2,3,0,1] row_mask:0xf bank_mask:0xf bound_ctrl:1
	v_add_f32_dpp v11, v11, v11 quad_perm:[2,3,0,1] row_mask:0xf bank_mask:0xf bound_ctrl:1
	ds_read_b128 v[110:113], v6 offset:38448
	v_add_f32_dpp v10, v10, v10 row_half_mirror row_mask:0xf bank_mask:0xf bound_ctrl:1
	v_add_f32_dpp v11, v11, v11 row_half_mirror row_mask:0xf bank_mask:0xf bound_ctrl:1
	ds_read_b128 v[114:117], v6 offset:38464
	v_add_f32_dpp v10, v10, v10 row_mirror row_mask:0xf bank_mask:0xf bound_ctrl:1
	v_add_f32_dpp v11, v11, v11 row_mirror row_mask:0xf bank_mask:0xf bound_ctrl:1
	v_pk_fma_f32 v[2:3], v[70:71], v[10:11], v[18:19] op_sel_hi:[1,0,1]
	v_pk_fma_f32 v[4:5], v[72:73], v[10:11], v[20:21] op_sel_hi:[1,0,1]
	ds_read2st64_b32 v[206:207], v7 offset0:30 offset1:31
	ds_read_b128 v[208:211], v8 offset:240
	s_waitcnt lgkmcnt(8)
	v_pk_mul_f32 v[12:13], v[2:3], v[78:79] op_sel_hi:[0,1]
	ds_read_b128 v[186:189], v6 offset:39680
	v_pk_mul_f32 v[18:19], v[94:95], v[118:119] op_sel:[0,1] op_sel_hi:[1,1]
	v_pk_fma_f32 v[12:13], v[2:3], v[80:81], v[12:13] op_sel:[1,0,0] op_sel_hi:[1,1,1]
	ds_read_b128 v[190:193], v6 offset:39696
	v_pk_mul_f32 v[20:21], v[96:97], v[118:119] op_sel:[0,1] op_sel_hi:[1,1]
	v_pk_fma_f32 v[12:13], v[4:5], v[82:83], v[12:13] op_sel_hi:[0,1,1]
	ds_read_b128 v[194:197], v6 offset:39712
	v_pk_fma_f32 v[18:19], v[2:3], v[86:87], v[18:19]
	v_pk_fma_f32 v[12:13], v[4:5], v[84:85], v[12:13] op_sel:[1,0,0] op_sel_hi:[1,1,1]
	v_pk_fma_f32 v[20:21], v[4:5], v[88:89], v[20:21]
	v_fmac_f32_e32 v11, v120, v10
	v_add_f32_dpp v12, v12, v12 quad_perm:[1,0,3,2] row_mask:0xf bank_mask:0xf bound_ctrl:1
	v_add_f32_dpp v13, v13, v13 quad_perm:[1,0,3,2] row_mask:0xf bank_mask:0xf bound_ctrl:1
	v_fmac_f32_e32 v11, v118, v121
	ds_read_b128 v[198:201], v6 offset:39728
	v_add_f32_dpp v12, v12, v12 quad_perm:[2,3,0,1] row_mask:0xf bank_mask:0xf bound_ctrl:1
	v_add_f32_dpp v13, v13, v13 quad_perm:[2,3,0,1] row_mask:0xf bank_mask:0xf bound_ctrl:1
	ds_read_b128 v[202:205], v6 offset:39744
	v_add_f32_dpp v12, v12, v12 row_half_mirror row_mask:0xf bank_mask:0xf bound_ctrl:1
	v_add_f32_dpp v13, v13, v13 row_half_mirror row_mask:0xf bank_mask:0xf bound_ctrl:1
	s_nop 0
	v_add_f32_dpp v12, v12, v12 row_mirror row_mask:0xf bank_mask:0xf bound_ctrl:1
	v_add_f32_dpp v13, v13, v13 row_mirror row_mask:0xf bank_mask:0xf bound_ctrl:1
	v_pk_fma_f32 v[2:3], v[90:91], v[12:13], v[18:19] op_sel_hi:[1,0,1]
	v_pk_fma_f32 v[4:5], v[92:93], v[12:13], v[20:21] op_sel_hi:[1,0,1]
	s_waitcnt lgkmcnt(5)
	v_pk_mul_f32 v[14:15], v[2:3], v[98:99] op_sel_hi:[0,1]
	v_pk_mul_f32 v[18:19], v[114:115], v[206:207] op_sel_hi:[1,0]
	v_pk_fma_f32 v[14:15], v[2:3], v[100:101], v[14:15] op_sel:[1,0,0] op_sel_hi:[1,1,1]
	v_pk_mul_f32 v[20:21], v[116:117], v[206:207] op_sel_hi:[1,0]
	v_pk_fma_f32 v[14:15], v[4:5], v[102:103], v[14:15] op_sel_hi:[0,1,1]
	v_pk_fma_f32 v[18:19], v[2:3], v[106:107], v[18:19]
	v_pk_fma_f32 v[14:15], v[4:5], v[104:105], v[14:15] op_sel:[1,0,0] op_sel_hi:[1,1,1]
	v_pk_fma_f32 v[20:21], v[4:5], v[108:109], v[20:21]
	v_fmac_f32_e32 v13, v122, v12
	v_add_f32_dpp v14, v14, v14 quad_perm:[1,0,3,2] row_mask:0xf bank_mask:0xf bound_ctrl:1
	v_add_f32_dpp v15, v15, v15 quad_perm:[1,0,3,2] row_mask:0xf bank_mask:0xf bound_ctrl:1
	v_fmac_f32_e32 v13, v119, v123
	ds_write2_b32 v22, v11, v13 offset0:192 offset1:208
	v_add_f32_dpp v14, v14, v14 quad_perm:[2,3,0,1] row_mask:0xf bank_mask:0xf bound_ctrl:1
	v_add_f32_dpp v15, v15, v15 quad_perm:[2,3,0,1] row_mask:0xf bank_mask:0xf bound_ctrl:1
	s_nop 0
	v_add_f32_dpp v14, v14, v14 row_half_mirror row_mask:0xf bank_mask:0xf bound_ctrl:1
	v_add_f32_dpp v15, v15, v15 row_half_mirror row_mask:0xf bank_mask:0xf bound_ctrl:1
	s_nop 0
	v_add_f32_dpp v14, v14, v14 row_mirror row_mask:0xf bank_mask:0xf bound_ctrl:1
	v_add_f32_dpp v15, v15, v15 row_mirror row_mask:0xf bank_mask:0xf bound_ctrl:1
	v_pk_fma_f32 v[2:3], v[110:111], v[14:15], v[18:19] op_sel_hi:[1,0,1]
	v_pk_fma_f32 v[4:5], v[112:113], v[14:15], v[20:21] op_sel_hi:[1,0,1]
	s_waitcnt lgkmcnt(1)
	v_pk_mul_f32 v[16:17], v[2:3], v[186:187] op_sel_hi:[0,1]
	v_pk_mul_f32 v[18:19], v[202:203], v[206:207] op_sel:[0,1] op_sel_hi:[1,1]
	v_pk_fma_f32 v[16:17], v[2:3], v[188:189], v[16:17] op_sel:[1,0,0] op_sel_hi:[1,1,1]
	v_pk_mul_f32 v[20:21], v[204:205], v[206:207] op_sel:[0,1] op_sel_hi:[1,1]
	v_pk_fma_f32 v[16:17], v[4:5], v[190:191], v[16:17] op_sel_hi:[0,1,1]
	v_pk_fma_f32 v[18:19], v[2:3], v[194:195], v[18:19]
	v_pk_fma_f32 v[16:17], v[4:5], v[192:193], v[16:17] op_sel:[1,0,0] op_sel_hi:[1,1,1]
	v_pk_fma_f32 v[20:21], v[4:5], v[196:197], v[20:21]
	v_fmac_f32_e32 v15, v208, v14
	v_add_f32_dpp v16, v16, v16 quad_perm:[1,0,3,2] row_mask:0xf bank_mask:0xf bound_ctrl:1
	v_add_f32_dpp v17, v17, v17 quad_perm:[1,0,3,2] row_mask:0xf bank_mask:0xf bound_ctrl:1
	v_fmac_f32_e32 v15, v206, v209
	v_add_f32_dpp v16, v16, v16 quad_perm:[2,3,0,1] row_mask:0xf bank_mask:0xf bound_ctrl:1
	v_add_f32_dpp v17, v17, v17 quad_perm:[2,3,0,1] row_mask:0xf bank_mask:0xf bound_ctrl:1
	s_nop 0
	v_add_f32_dpp v16, v16, v16 row_half_mirror row_mask:0xf bank_mask:0xf bound_ctrl:1
	v_add_f32_dpp v17, v17, v17 row_half_mirror row_mask:0xf bank_mask:0xf bound_ctrl:1
	s_nop 0
	v_add_f32_dpp v16, v16, v16 row_mirror row_mask:0xf bank_mask:0xf bound_ctrl:1
	v_add_f32_dpp v17, v17, v17 row_mirror row_mask:0xf bank_mask:0xf bound_ctrl:1
	v_pk_fma_f32 v[2:3], v[198:199], v[16:17], v[18:19] op_sel_hi:[1,0,1]
	v_pk_fma_f32 v[4:5], v[200:201], v[16:17], v[20:21] op_sel_hi:[1,0,1]
	v_fmac_f32_e32 v17, v210, v16
	v_fmac_f32_e32 v17, v207, v211
	ds_write2_b32 v22, v15, v17 offset0:224 offset1:240
	s_add_i32 s0, s0, 1
	s_cmpk_lg_i32 s0, 0x80
	s_waitcnt lgkmcnt(0)
	s_barrier
	s_cbranch_scc1 .LBB0_726

.LBB0_768:
	v_lshlrev_b32_e32 v162, 16, v122
	v_lshlrev_b32_e32 v154, 16, v100
	v_and_b32_e32 v155, 0xffff0000, v100
	v_lshlrev_b32_e32 v56, 16, v101
	v_lshlrev_b32_e32 v16, 16, v111
	v_lshlrev_b32_e32 v163, 16, v105
	v_and_b32_e32 v100, 0xffff0000, v105
	v_lshlrev_b32_e32 v158, 16, v104
	v_and_b32_e32 v159, 0xffff0000, v104
	v_lshlrev_b32_e32 v104, 16, v108
	v_and_b32_e32 v105, 0xffff0000, v108
	v_lshlrev_b32_e32 v153, 16, v109
	v_and_b32_e32 v167, 0xffff0000, v122
	v_and_b32_e32 v165, 0xffff0000, v101
	v_mul_f32_e32 v101, 0xbfb8aa3b, v162
	v_lshlrev_b32_e32 v156, 16, v110
	v_and_b32_e32 v157, 0xffff0000, v110
	v_and_b32_e32 v161, 0xffff0000, v111
	v_and_b32_e32 v160, 0xffff0000, v109
	v_lshlrev_b32_e32 v108, 16, v102
	v_and_b32_e32 v109, 0xffff0000, v102
	v_lshlrev_b32_e32 v110, 16, v106
	v_and_b32_e32 v111, 0xffff0000, v106
	v_lshlrev_b32_e32 v173, 16, v123
	v_and_b32_e32 v123, 0xffff0000, v123
	v_pk_add_f32 v[168:169], v[104:105], v[158:159] neg_lo:[0,1] neg_hi:[0,1]
	v_exp_f32_e32 v104, v101
	v_mul_f32_e32 v101, 0xbfb8aa3b, v167
	v_sub_f32_e32 v172, v16, v56
	v_sub_f32_e32 v16, v153, v163
	v_lshlrev_b32_e32 v102, 16, v103
	v_and_b32_e32 v103, 0xffff0000, v103
	v_lshlrev_b32_e32 v106, 16, v107
	v_and_b32_e32 v107, 0xffff0000, v107
	v_lshlrev_b32_e32 v184, 16, v121
	v_pk_add_f32 v[110:111], v[110:111], v[108:109] neg_lo:[0,1] neg_hi:[0,1]
	v_exp_f32_e32 v105, v101
	v_fmac_f32_e32 v163, v24, v16
	v_mul_f32_e32 v16, 0xbfb8aa3b, v173
	v_mul_f32_e32 v101, 0xbfb8aa3b, v123
	v_pk_fma_f32 v[108:109], v[18:19], v[110:111], v[108:109]
	v_pk_add_f32 v[110:111], v[106:107], v[102:103] neg_lo:[0,1] neg_hi:[0,1]
	v_exp_f32_e32 v106, v16
	v_sub_f32_e32 v16, v160, v100
	v_exp_f32_e32 v107, v101
	v_add_f32_e32 v101, -1.0, v184
	v_pk_fma_f32 v[110:111], v[20:21], v[110:111], v[102:103]
	v_pk_add_f32 v[102:103], v[156:157], v[154:155] neg_lo:[0,1] neg_hi:[0,1]
	v_mul_f32_e32 v101, v32, v101
	v_fmac_f32_e32 v100, v25, v16
	v_pk_fma_f32 v[102:103], v[14:15], v[102:103], v[154:155]
	v_pk_mul_f32 v[156:157], v[76:77], v[100:101]
	v_pk_add_f32 v[154:155], v[76:77], v[100:101]
	v_mul_f32_e32 v175, v28, v163
	v_mov_b32_e32 v157, v155
	v_pk_fma_f32 v[154:155], v[22:23], v[168:169], v[158:159]
	v_mov_b32_e32 v174, v156
	v_pk_mul_f32 v[158:159], v[26:27], v[154:155]
	v_pk_mul_f32 v[176:177], v[174:175], v[174:175]
	v_pk_mul_f32 v[168:169], v[158:159], v[158:159]
	v_and_b32_e32 v164, 0xffff0000, v120
	v_add_f32_e32 v101, v168, v169
	v_add_f32_e32 v101, v177, v101
	v_add_f32_e32 v101, v176, v101
	v_pk_mov_b32 v[178:179], v[164:165], v[164:165] op_sel:[1,0]
	v_lshlrev_b32_e32 v122, 16, v120
	v_add_f32_dpp v101, v101, v101 quad_perm:[1,0,3,2] row_mask:0xf bank_mask:0xf bound_ctrl:1
	v_mov_b32_e32 v123, v179
	v_pk_add_f32 v[180:181], v[122:123], -1.0 op_sel_hi:[1,0]
	v_add_f32_dpp v101, v101, v101 quad_perm:[2,3,0,1] row_mask:0xf bank_mask:0xf bound_ctrl:1
	v_and_b32_e32 v166, 0xffff0000, v121
	v_pk_fma_f32 v[180:181], v[30:31], v[180:181], 1.0 op_sel_hi:[1,1,0]
	v_add_f32_dpp v101, v101, v101 row_half_mirror row_mask:0xf bank_mask:0xf bound_ctrl:1
	v_add_f32_e32 v173, -1.0, v166
	v_pk_mul_f32 v[154:155], v[180:181], v[154:155]
	v_add_f32_dpp v101, v101, v101 row_mirror row_mask:0xf bank_mask:0xf bound_ctrl:1
	v_max_f32_e32 v101, 0x179abe15, v101
	v_rsq_f32_e32 v162, v101
	v_mov_b32_e32 v16, v103
	v_pk_fma_f32 v[172:173], v[74:75], v[172:173], v[56:57]
	v_fma_f32 v179, v154, v102, 0
	v_pk_mul_f32 v[168:169], v[158:159], v[162:163] op_sel_hi:[1,0]
	v_mov_b32_e32 v180, v17
	v_mov_b32_e32 v160, v169
	v_mul_f32_e32 v158, v168, v122
	v_pk_mul_f32 v[176:177], v[160:161], v[164:165]
	v_pk_add_f32 v[160:161], v[160:161], v[164:165] neg_lo:[0,1] neg_hi:[0,1]
	v_fma_f32 v122, v102, v158, 0
	v_mov_b32_e32 v177, v161
	v_mov_b32_e32 v181, v155
	v_mov_b32_e32 v160, v161
	v_mov_b32_e32 v161, v103
	v_mov_b32_e32 v123, v165
	v_mov_b32_e32 v167, v172
	v_mul_f32_e32 v56, v154, v102
	v_pk_fma_f32 v[182:183], v[16:17], v[176:177], v[122:123]
	v_pk_fma_f32 v[178:179], v[180:181], v[160:161], v[178:179]
	v_pk_mul_f32 v[180:181], v[156:157], v[162:163]
	v_mul_f32_e64 v164, v175, -v162
	v_pk_mul_f32 v[120:121], v[104:105], v[102:103]
	v_fma_f32 v56, v10, v56, 0
	v_pk_mul_f32 v[102:103], v[154:155], v[102:103]
	v_mul_f32_e64 v160, -v164, v184
	v_pk_mul_f32 v[174:175], v[180:181], v[166:167]
	v_mov_b32_e32 v161, v100
	v_mov_b32_e32 v100, v172
	v_mov_b32_e32 v101, v183
	v_fmac_f32_e32 v56, v11, v103
	v_pk_mul_f32 v[156:157], v[172:173], v[160:161]
	v_pk_mul_f32 v[122:123], v[106:107], v[100:101]
	v_pk_mul_f32 v[100:101], v[178:179], v[174:175]
	v_pk_fma_f32 v[102:103], v[180:181], v[166:167], v[178:179]
	v_pk_mul_f32 v[162:163], v[156:157], v[182:183]
	v_mov_b32_e32 v101, v103
	v_pk_fma_f32 v[102:103], v[172:173], v[160:161], v[182:183]
	s_and_b32 s0, s63, 1
	v_mov_b32_e32 v103, v163
	v_pk_add_f32 v[100:101], v[102:103], v[100:101]
	s_mul_i32 s1, s0, 0xa000
	v_fmac_f32_e32 v56, v12, v175
	v_mov_b32_dpp v102, v100 quad_perm:[1,0,3,2] row_mask:0xf bank_mask:0xf bound_ctrl:1
	v_mov_b32_dpp v103, v101 quad_perm:[1,0,3,2] row_mask:0xf bank_mask:0xf bound_ctrl:1
	v_pk_add_f32 v[100:101], v[100:101], v[102:103]
	v_add_u32_e32 v69, s1, v138
	v_fmac_f32_e32 v56, v13, v163
	v_mov_b32_dpp v102, v100 quad_perm:[2,3,0,1] row_mask:0xf bank_mask:0xf bound_ctrl:1
	v_mov_b32_dpp v103, v101 quad_perm:[2,3,0,1] row_mask:0xf bank_mask:0xf bound_ctrl:1
	v_lshl_add_u32 v0, s0, 13, v136
	v_add_u32_e32 v69, v69, v145
	v_pk_add_f32 v[100:101], v[100:101], v[102:103]
	v_add_f32_dpp v16, v56, v56 quad_perm:[1,0,3,2] row_mask:0xf bank_mask:0xf bound_ctrl:1
	v_xor_b32_e32 v163, 0x80000000, v169
	v_xor_b32_e32 v162, 0x80000000, v168
	v_xor_b32_e32 v165, 0x80000000, v180
	s_lshl_b32 s8, s0, 8
	v_mov_b32_dpp v102, v100 row_half_mirror row_mask:0xf bank_mask:0xf bound_ctrl:1
	v_mov_b32_dpp v103, v101 row_half_mirror row_mask:0xf bank_mask:0xf bound_ctrl:1
	v_add_f32_dpp v16, v16, v16 quad_perm:[2,3,0,1] row_mask:0xf bank_mask:0xf bound_ctrl:1
	ds_write2_b32 v69, v162, v120 offset1:1
	ds_write2_b32 v69, v163, v121 offset0:2 offset1:3
	ds_write2_b32 v69, v164, v122 offset0:4 offset1:5
	ds_write2_b32 v69, v165, v123 offset0:6 offset1:7
	ds_write_b128 v69, v[104:107] offset:32
	v_mov_b32_e32 v159, v176
	v_mov_b32_e32 v161, v174
	v_mov_b32_e32 v156, v181
	v_add_u32_e32 v104, v0, v146
	s_add_i32 s46, s8, 0
	v_pk_add_f32 v[100:101], v[100:101], v[102:103]
	v_add_f32_dpp v16, v16, v16 row_half_mirror row_mask:0xf bank_mask:0xf bound_ctrl:1
	ds_write_b128 v69, v[158:161] offset:48
	ds_write_b128 v69, v[154:157] offset:64
	ds_write_b128 v104, v[108:111]
	v_cndmask_b32_e64 v104, 0, 1, s[38:39]
	s_add_i32 s46, s46, 0x18000
	v_mov_b32_dpp v102, v100 row_mirror row_mask:0xf bank_mask:0xf bound_ctrl:1
	v_mov_b32_dpp v103, v101 row_mirror row_mask:0xf bank_mask:0xf bound_ctrl:1
	v_mov_b32_dpp v56, v16 row_mirror row_mask:0xf bank_mask:0xf bound_ctrl:1
	v_cmp_ne_u32_e64 s[8:9], 1, v104
	s_and_saveexec_b64 s[0:1], s[6:7]
	s_cbranch_execz .LBB0_771
	v_add_u32_e32 v104, s46, v147
	v_pk_add_f32 v[100:101], v[100:101], v[102:103]
	s_and_b64 vcc, exec, s[8:9]
	ds_write_b64 v104, v[100:101]
	s_cbranch_vccnz .LBB0_771
	v_lshl_add_u64 v[100:101], s[66:67], 0, v[78:79]
	v_add_co_u32_e32 v100, vcc, 0x1f000000, v100
	v_add_f32_e32 v16, v16, v56
	s_nop 0
	v_addc_co_u32_e32 v101, vcc, 0, v101, vcc
	global_store_dword v[100:101], v16, off

.LBB0_773:
	v_lshlrev_b32_e32 v132, 16, v86
	v_and_b32_e32 v133, 0xffff0000, v86
	v_lshlrev_b32_e32 v134, 16, v98
	v_and_b32_e32 v135, 0xffff0000, v98
	v_lshlrev_b32_e32 v157, 16, v97
	v_and_b32_e32 v86, 0xffff0000, v97
	v_lshlrev_b32_e32 v154, 16, v96
	v_and_b32_e32 v155, 0xffff0000, v96
	v_lshlrev_b32_e32 v96, 16, v94
	v_and_b32_e32 v97, 0xffff0000, v94
	v_lshlrev_b32_e32 v98, 16, v95
	v_and_b32_e32 v153, 0xffff0000, v95
	v_lshlrev_b32_e32 v94, 16, v88
	v_and_b32_e32 v95, 0xffff0000, v88
	v_lshlrev_b32_e32 v88, 16, v90
	v_lshlrev_b32_e32 v56, 16, v87
	v_lshlrev_b32_e32 v16, 16, v99
	v_lshlrev_b32_e32 v158, 16, v92
	v_and_b32_e32 v159, 0xffff0000, v92
	v_lshlrev_b32_e32 v160, 16, v89
	v_and_b32_e32 v161, 0xffff0000, v89
	v_and_b32_e32 v89, 0xffff0000, v90
	v_lshlrev_b32_e32 v164, 16, v84
	v_and_b32_e32 v166, 0xffff0000, v84
	v_lshlrev_b32_e32 v178, 16, v85
	v_and_b32_e32 v84, 0xffff0000, v85
	v_mul_f32_e32 v85, 0xbfb8aa3b, v88
	v_lshlrev_b32_e32 v156, 16, v91
	v_and_b32_e32 v165, 0xffff0000, v91
	v_pk_add_f32 v[90:91], v[158:159], v[94:95] neg_lo:[0,1] neg_hi:[0,1]
	v_exp_f32_e32 v88, v85
	v_mul_f32_e32 v85, 0xbfb8aa3b, v89
	v_sub_f32_e32 v158, v16, v56
	v_sub_f32_e32 v16, v98, v157
	v_exp_f32_e32 v89, v85
	v_fmac_f32_e32 v157, v24, v16
	v_mul_f32_e32 v16, 0xbfb8aa3b, v156
	v_mul_f32_e32 v85, 0xbfb8aa3b, v165
	v_lshlrev_b32_e32 v162, 16, v93
	v_and_b32_e32 v163, 0xffff0000, v93
	v_pk_fma_f32 v[92:93], v[18:19], v[90:91], v[94:95]
	v_exp_f32_e32 v90, v16
	v_sub_f32_e32 v16, v153, v86
	v_exp_f32_e32 v91, v85
	v_add_f32_e32 v85, -1.0, v178
	v_and_b32_e32 v167, 0xffff0000, v87
	v_pk_add_f32 v[168:169], v[96:97], v[154:155] neg_lo:[0,1] neg_hi:[0,1]
	v_pk_add_f32 v[94:95], v[162:163], v[160:161] neg_lo:[0,1] neg_hi:[0,1]
	v_pk_add_f32 v[96:97], v[134:135], v[132:133] neg_lo:[0,1] neg_hi:[0,1]
	v_mul_f32_e32 v87, v32, v85
	v_fmac_f32_e32 v86, v25, v16
	v_pk_fma_f32 v[94:95], v[20:21], v[94:95], v[160:161]
	v_pk_fma_f32 v[134:135], v[14:15], v[96:97], v[132:133]
	v_pk_mul_f32 v[160:161], v[76:77], v[86:87]
	v_pk_add_f32 v[132:133], v[76:77], v[86:87]
	v_mul_f32_e32 v163, v28, v157
	v_mov_b32_e32 v161, v133
	v_pk_fma_f32 v[132:133], v[22:23], v[168:169], v[154:155]
	v_mov_b32_e32 v162, v160
	v_pk_mul_f32 v[154:155], v[26:27], v[132:133]
	v_pk_mul_f32 v[172:173], v[162:163], v[162:163]
	v_pk_mul_f32 v[168:169], v[154:155], v[154:155]
	v_pk_mov_b32 v[174:175], v[166:167], v[166:167] op_sel:[1,0]
	v_add_f32_e32 v87, v168, v169
	v_add_f32_e32 v87, v173, v87
	v_add_f32_e32 v87, v172, v87
	v_mov_b32_e32 v165, v175
	v_pk_add_f32 v[176:177], v[164:165], -1.0 op_sel_hi:[1,0]
	v_add_f32_dpp v87, v87, v87 quad_perm:[1,0,3,2] row_mask:0xf bank_mask:0xf bound_ctrl:1
	v_and_b32_e32 v99, 0xffff0000, v99
	v_pk_fma_f32 v[176:177], v[30:31], v[176:177], 1.0 op_sel_hi:[1,1,0]
	v_add_f32_dpp v87, v87, v87 quad_perm:[2,3,0,1] row_mask:0xf bank_mask:0xf bound_ctrl:1
	v_add_f32_e32 v159, -1.0, v84
	v_pk_mul_f32 v[132:133], v[176:177], v[132:133]
	v_add_f32_dpp v87, v87, v87 row_half_mirror row_mask:0xf bank_mask:0xf bound_ctrl:1
	v_mov_b32_e32 v16, v135
	v_pk_fma_f32 v[158:159], v[74:75], v[158:159], v[56:57]
	v_add_f32_dpp v87, v87, v87 row_mirror row_mask:0xf bank_mask:0xf bound_ctrl:1
	v_max_f32_e32 v87, 0x179abe15, v87
	v_rsq_f32_e32 v156, v87
	v_fma_f32 v175, v132, v134, 0
	v_mov_b32_e32 v176, v17
	v_mov_b32_e32 v177, v133
	v_pk_mul_f32 v[168:169], v[154:155], v[156:157] op_sel_hi:[1,0]
	v_mov_b32_e32 v165, v167
	v_mov_b32_e32 v98, v169
	v_mul_f32_e32 v154, v168, v164
	v_pk_mul_f32 v[172:173], v[98:99], v[166:167]
	v_pk_add_f32 v[98:99], v[98:99], v[166:167] neg_lo:[0,1] neg_hi:[0,1]
	v_fma_f32 v164, v134, v154, 0
	v_mov_b32_e32 v173, v99
	v_mov_b32_e32 v98, v99
	v_mov_b32_e32 v99, v135
	v_mov_b32_e32 v85, v158
	v_mul_f32_e32 v56, v132, v134
	v_pk_fma_f32 v[164:165], v[16:17], v[172:173], v[164:165]
	v_pk_fma_f32 v[166:167], v[176:177], v[98:99], v[174:175]
	v_pk_mul_f32 v[174:175], v[160:161], v[156:157]
	v_mul_f32_e64 v160, v163, -v156
	v_pk_mul_f32 v[96:97], v[88:89], v[134:135]
	v_fma_f32 v56, v10, v56, 0
	v_pk_mul_f32 v[134:135], v[132:133], v[134:135]
	v_mul_f32_e64 v156, -v160, v178
	v_pk_mul_f32 v[162:163], v[174:175], v[84:85]
	v_mov_b32_e32 v157, v86
	v_mov_b32_e32 v86, v158
	v_mov_b32_e32 v87, v165
	v_fmac_f32_e32 v56, v11, v135
	v_pk_mul_f32 v[134:135], v[158:159], v[156:157]
	v_pk_mul_f32 v[98:99], v[90:91], v[86:87]
	v_pk_mul_f32 v[86:87], v[166:167], v[162:163]
	v_pk_fma_f32 v[84:85], v[174:175], v[84:85], v[166:167]
	v_fmac_f32_e32 v56, v12, v163
	v_mov_b32_e32 v87, v85
	v_pk_fma_f32 v[84:85], v[158:159], v[156:157], v[164:165]
	v_pk_mul_f32 v[158:159], v[134:135], v[164:165]
	v_xor_b32_e32 v161, 0x80000000, v174
	v_mov_b32_e32 v85, v159
	v_pk_add_f32 v[84:85], v[84:85], v[86:87]
	v_fmac_f32_e32 v56, v13, v159
	v_xor_b32_e32 v159, 0x80000000, v169
	v_mov_b32_dpp v86, v84 quad_perm:[1,0,3,2] row_mask:0xf bank_mask:0xf bound_ctrl:1
	v_mov_b32_dpp v87, v85 quad_perm:[1,0,3,2] row_mask:0xf bank_mask:0xf bound_ctrl:1
	v_pk_add_f32 v[84:85], v[84:85], v[86:87]
	v_add_f32_dpp v16, v56, v56 quad_perm:[1,0,3,2] row_mask:0xf bank_mask:0xf bound_ctrl:1
	v_xor_b32_e32 v158, 0x80000000, v168
	v_mov_b32_dpp v86, v84 quad_perm:[2,3,0,1] row_mask:0xf bank_mask:0xf bound_ctrl:1
	v_mov_b32_dpp v87, v85 quad_perm:[2,3,0,1] row_mask:0xf bank_mask:0xf bound_ctrl:1
	v_pk_add_f32 v[84:85], v[84:85], v[86:87]
	v_add_f32_dpp v16, v16, v16 quad_perm:[2,3,0,1] row_mask:0xf bank_mask:0xf bound_ctrl:1
	v_mov_b32_e32 v155, v172
	v_mov_b32_dpp v86, v84 row_half_mirror row_mask:0xf bank_mask:0xf bound_ctrl:1
	v_mov_b32_dpp v87, v85 row_half_mirror row_mask:0xf bank_mask:0xf bound_ctrl:1
	v_pk_add_f32 v[84:85], v[84:85], v[86:87]
	v_add_f32_dpp v16, v16, v16 row_half_mirror row_mask:0xf bank_mask:0xf bound_ctrl:1
	v_mov_b32_e32 v157, v162
	v_mov_b32_dpp v86, v84 row_mirror row_mask:0xf bank_mask:0xf bound_ctrl:1
	v_mov_b32_dpp v87, v85 row_mirror row_mask:0xf bank_mask:0xf bound_ctrl:1
	v_mov_b32_dpp v56, v16 row_mirror row_mask:0xf bank_mask:0xf bound_ctrl:1
	v_mov_b32_e32 v134, v175
	v_add_u32_e32 v0, v0, v148
	v_add_u32_e32 v253, 0x5000, v69
	ds_write2_b32 v253, v158, v96 offset1:1
	ds_write2_b32 v253, v159, v97 offset0:2 offset1:3
	ds_write2_b32 v253, v160, v98 offset0:4 offset1:5
	ds_write2_b32 v253, v161, v99 offset0:6 offset1:7
	ds_write_b128 v69, v[88:91] offset:20512
	ds_write_b128 v69, v[154:157] offset:20528
	ds_write_b128 v69, v[132:135] offset:20544
	ds_write_b128 v0, v[92:95]
	s_and_saveexec_b64 s[0:1], s[6:7]
	s_cbranch_execz .LBB0_776
	v_add_u32_e32 v0, s46, v149
	v_pk_add_f32 v[84:85], v[84:85], v[86:87]
	s_and_b64 vcc, exec, s[8:9]
	ds_write_b64 v0, v[84:85]
	s_cbranch_vccnz .LBB0_776
	v_lshl_add_u64 v[84:85], s[66:67], 0, v[78:79]
	v_add_co_u32_e32 v84, vcc, 0x1f000000, v84
	v_add_f32_e32 v0, v16, v56
	s_nop 0
	v_addc_co_u32_e32 v85, vcc, 0, v85, vcc
	global_store_dword v[84:85], v0, off offset:1024
